# GEMM loops: an extra s_setprio 0 / s_setprio 1 drop point after every 8 MFMAs (was every 16)
# speedup vs baseline: 1.0115x; 1.0022x over previous
; #define PG8_STAGE(bufoff, gbase, voff) do { _Pragma("unroll") for (int _i = 0; _i < 2; ++_i) \
;         __builtin_amdgcn_global_load_lds((const unsigned*)((const char*)(gbase) + (voff)[_i]), (LAS unsigned*)(lds + (bufoff) + ldsw + _i * 8192), 16, 0, 0); } while (0)
; #define PG8_LDA(dst, b, h) do { _Pragma("unroll") for (int m = 0; m < 4; ++m) _Pragma("unroll") for (int k = 0; k < 2; ++k) dst[m][k] = *(const LAS bf16x8*)(lds + PG8_SA(b, h) + aoff + m * 2048 + k * 1024); } while (0)
; #define PG8_LDB(dst, b, h) do { _Pragma("unroll") for (int n = 0; n < 2; ++n) _Pragma("unroll") for (int k = 0; k < 2; ++k) dst[n][k] = *(const LAS bf16x8*)(lds + PG8_SB(b, h) + boff + n * 2048 + k * 1024); } while (0)
; #define PG8_MMA(ai, bj, At, Bt) do { __builtin_amdgcn_s_setprio(1); _Pragma("unroll") for (int m = 0; m < 4; ++m) _Pragma("unroll") for (int n = 0; n < 2; ++n) _Pragma("unroll") for (int k = 0; k < 2; ++k) \
;         acc[ai][bj][m][n] = __builtin_amdgcn_mfma_f32_16x16x32_bf16(Bt[n][k], At[m][k], acc[ai][bj][m][n], 0, 0, 0); __builtin_amdgcn_s_setprio(0); } while (0)
; #define PG8_WAIT_V(n) asm volatile("s_waitcnt vmcnt(" #n ")" ::: "memory")
; #define PG8_WAIT_L(n) asm volatile("s_waitcnt lgkmcnt(" #n ")" ::: "memory")
; #define PG8_BAR __builtin_amdgcn_s_barrier()
; #define PG8_SCHED __builtin_amdgcn_sched_barrier(0)
; template <class Epi, class Sched>
; __device__ __forceinline__ void gemm_phase(LAS unsigned char* lds, const Gemm g, const Sched& S, const Epi& E, const int wave_s) {
;     ...
;             const bool last = (t == nt - 2);
;             const char* a1 = cA + (size_t)(t + 1) * kstep;
;             const char* a2 = last ? nA : cA + (size_t)(t + 2) * kstep; const char* b2 = last ? nB : cB + (size_t)(t + 2) * kstep;
;             const char* a3 = a2 + kstep; const char* b3 = b2 + kstep;
;             PG8_LDB(B0, 0, 0); PG8_LDB(B1, 0, 1); PG8_SCHED; PG8_LDA(At, 0, 0); PG8_STAGE(PG8_SA(1, 1), a1 + hstepA, voffA);
;             PG8_WAIT_V(8); PG8_WAIT_L(0); PG8_BAR; PG8_MMA(0, 0, At, B0); PG8_MMA(0, 1, At, B1); PG8_BAR; PG8_SCHED;
;             PG8_LDA(At, 0, 1); PG8_STAGE(PG8_SB(0, 0), b2, voffB); PG8_STAGE(PG8_SB(0, 1), b2 + hstepB, voffB); PG8_STAGE(PG8_SA(0, 0), a2, voffA);
;             PG8_WAIT_V(8); PG8_WAIT_L(0); PG8_BAR; PG8_MMA(1, 0, At, B0); PG8_MMA(1, 1, At, B1); PG8_BAR; PG8_SCHED;
.LBB0_125:
	ds_read_b128 v[152:155], v149
	ds_read_b128 v[156:159], v149 offset:1024
	ds_read_b128 v[160:163], v149 offset:2048
	ds_read_b128 v[164:167], v149 offset:3072
	ds_read_b128 v[168:171], v150
	ds_read_b128 v[172:175], v150 offset:1024
	ds_read_b128 v[176:179], v150 offset:2048
	ds_read_b128 v[180:183], v150 offset:3072
	s_add_u32 s4, s44, 0xfffc0080
	s_addc_u32 s5, s45, -1
	s_cmp_eq_u32 s65, 12
	s_cselect_b32 s47, s29, s5
	s_cselect_b32 s46, s61, s4
	s_cselect_b32 s5, s27, s64
	s_cselect_b32 s4, s62, s63
	v_lshl_add_u64 v[144:145], s[44:45], 0, v[136:137]
	s_add_i32 m0, s33, 0xc000
	ds_read_b128 v[184:187], v151
	ds_read_b128 v[188:191], v151 offset:1024
	ds_read_b128 v[192:195], v151 offset:2048
	ds_read_b128 v[196:199], v151 offset:3072
	ds_read_b128 v[200:203], v151 offset:4096
	ds_read_b128 v[204:207], v151 offset:5120
	ds_read_b128 v[210:213], v151 offset:6144
	ds_read_b128 v[214:217], v151 offset:7168
	global_load_lds_dwordx4 v[144:145], off
	v_lshl_add_u64 v[144:145], s[44:45], 0, v[138:139]
	s_add_i32 m0, s33, 0xe000
	s_nop 0
	global_load_lds_dwordx4 v[144:145], off
	s_waitcnt vmcnt(8) lgkmcnt(0)
	s_barrier
	s_setprio 1
	v_mfma_f32_16x16x32_bf16 v[124:127], v[152:155], v[184:187], v[124:127]
	v_mfma_f32_16x16x32_bf16 v[120:123], v[160:163], v[184:187], v[120:123]
	v_mfma_f32_16x16x32_bf16 v[116:119], v[152:155], v[192:195], v[116:119]
	v_mfma_f32_16x16x32_bf16 v[108:111], v[160:163], v[192:195], v[108:111]
	v_mfma_f32_16x16x32_bf16 v[100:103], v[152:155], v[200:203], v[100:103]
	v_mfma_f32_16x16x32_bf16 v[92:95], v[160:163], v[200:203], v[92:95]
	v_mfma_f32_16x16x32_bf16 v[84:87], v[152:155], v[210:213], v[84:87]
	v_mfma_f32_16x16x32_bf16 v[76:79], v[160:163], v[210:213], v[76:79]
	s_setprio 0
	s_setprio 1
	v_mfma_f32_16x16x32_bf16 v[124:127], v[156:159], v[188:191], v[124:127]
	v_mfma_f32_16x16x32_bf16 v[120:123], v[164:167], v[188:191], v[120:123]
	v_mfma_f32_16x16x32_bf16 v[116:119], v[156:159], v[196:199], v[116:119]
	v_mfma_f32_16x16x32_bf16 v[108:111], v[164:167], v[196:199], v[108:111]
	v_mfma_f32_16x16x32_bf16 v[100:103], v[156:159], v[204:207], v[100:103]
	v_mfma_f32_16x16x32_bf16 v[92:95], v[164:167], v[204:207], v[92:95]
	v_mfma_f32_16x16x32_bf16 v[84:87], v[156:159], v[214:217], v[84:87]
	v_mfma_f32_16x16x32_bf16 v[76:79], v[164:167], v[214:217], v[76:79]
	s_setprio 0
	s_setprio 1
	v_mfma_f32_16x16x32_bf16 v[112:115], v[168:171], v[184:187], v[112:115]
	v_mfma_f32_16x16x32_bf16 v[104:107], v[176:179], v[184:187], v[104:107]
	v_mfma_f32_16x16x32_bf16 v[96:99], v[168:171], v[192:195], v[96:99]
	v_mfma_f32_16x16x32_bf16 v[88:91], v[176:179], v[192:195], v[88:91]
	v_mfma_f32_16x16x32_bf16 v[80:83], v[168:171], v[200:203], v[80:83]
	v_mfma_f32_16x16x32_bf16 v[72:75], v[176:179], v[200:203], v[72:75]
	v_mfma_f32_16x16x32_bf16 v[68:71], v[168:171], v[210:213], v[68:71]
	v_mfma_f32_16x16x32_bf16 v[64:67], v[176:179], v[210:213], v[64:67]
	s_setprio 0
	s_setprio 1
	v_mfma_f32_16x16x32_bf16 v[112:115], v[172:175], v[188:191], v[112:115]
	v_mfma_f32_16x16x32_bf16 v[104:107], v[180:183], v[188:191], v[104:107]
	v_mfma_f32_16x16x32_bf16 v[96:99], v[172:175], v[196:199], v[96:99]
	v_mfma_f32_16x16x32_bf16 v[88:91], v[180:183], v[196:199], v[88:91]
	v_mfma_f32_16x16x32_bf16 v[80:83], v[172:175], v[204:207], v[80:83]
	v_mfma_f32_16x16x32_bf16 v[72:75], v[180:183], v[204:207], v[72:75]
	v_mfma_f32_16x16x32_bf16 v[68:71], v[172:175], v[214:217], v[68:71]
	v_mfma_f32_16x16x32_bf16 v[64:67], v[180:183], v[214:217], v[64:67]
	s_setprio 0
	s_barrier
	s_add_i32 s66, s53, s81
	v_lshl_add_u64 v[144:145], s[4:5], 0, v[130:131]
	s_mov_b32 m0, s66
	ds_read_b128 v[184:187], v151 offset:16384
	ds_read_b128 v[188:191], v151 offset:17408
	ds_read_b128 v[192:195], v151 offset:18432
	ds_read_b128 v[196:199], v151 offset:19456
	ds_read_b128 v[200:203], v151 offset:20480
	ds_read_b128 v[204:207], v151 offset:21504
	ds_read_b128 v[210:213], v151 offset:22528
	ds_read_b128 v[214:217], v151 offset:23552
	global_load_lds_dwordx4 v[144:145], off
	s_add_i32 m0, s66, 0x2000
	s_add_u32 s66, s4, 0x40000
	v_lshl_add_u64 v[218:219], s[4:5], 0, v[134:135]
	s_addc_u32 s67, s5, 0
	s_add_i32 s68, s54, s81
	global_load_lds_dwordx4 v[218:219], off
	v_lshl_add_u64 v[220:221], s[66:67], 0, v[130:131]
	s_mov_b32 m0, s68
	v_lshl_add_u64 v[222:223], s[46:47], 0, v[132:133]
	global_load_lds_dwordx4 v[220:221], off
	v_lshl_add_u64 v[220:221], s[66:67], 0, v[134:135]
	s_add_i32 m0, s68, 0x2000
	s_nop 0
	global_load_lds_dwordx4 v[220:221], off
	v_lshl_add_u64 v[220:221], s[46:47], 0, v[128:129]
	s_mov_b32 m0, s33
	s_nop 0
	global_load_lds_dwordx4 v[220:221], off
	s_mov_b32 m0, s35
	s_nop 0
	global_load_lds_dwordx4 v[222:223], off
	s_waitcnt vmcnt(8) lgkmcnt(0)
	s_barrier
; #define PG8_STAGE(bufoff, gbase, voff) do { _Pragma("unroll") for (int _i = 0; _i < 2; ++_i) \
;         __builtin_amdgcn_global_load_lds((const unsigned*)((const char*)(gbase) + (voff)[_i]), (LAS unsigned*)(lds + (bufoff) + ldsw + _i * 8192), 16, 0, 0); } while (0)
; #define PG8_LDA(dst, b, h) do { _Pragma("unroll") for (int m = 0; m < 4; ++m) _Pragma("unroll") for (int k = 0; k < 2; ++k) dst[m][k] = *(const LAS bf16x8*)(lds + PG8_SA(b, h) + aoff + m * 2048 + k * 1024); } while (0)
; #define PG8_LDB(dst, b, h) do { _Pragma("unroll") for (int n = 0; n < 2; ++n) _Pragma("unroll") for (int k = 0; k < 2; ++k) dst[n][k] = *(const LAS bf16x8*)(lds + PG8_SB(b, h) + boff + n * 2048 + k * 1024); } while (0)
; #define PG8_MMA(ai, bj, At, Bt) do { __builtin_amdgcn_s_setprio(1); _Pragma("unroll") for (int m = 0; m < 4; ++m) _Pragma("unroll") for (int n = 0; n < 2; ++n) _Pragma("unroll") for (int k = 0; k < 2; ++k) \
;         acc[ai][bj][m][n] = __builtin_amdgcn_mfma_f32_16x16x32_bf16(Bt[n][k], At[m][k], acc[ai][bj][m][n], 0, 0, 0); __builtin_amdgcn_s_setprio(0); } while (0)
; #define PG8_WAIT_V(n) asm volatile("s_waitcnt vmcnt(" #n ")" ::: "memory")
; #define PG8_WAIT_L(n) asm volatile("s_waitcnt lgkmcnt(" #n ")" ::: "memory")
; #define PG8_BAR __builtin_amdgcn_s_barrier()
; #define PG8_SCHED __builtin_amdgcn_sched_barrier(0)
; template <class Epi, class Sched>
; __device__ __forceinline__ void gemm_phase(LAS unsigned char* lds, const Gemm g, const Sched& S, const Epi& E, const int wave_s) {
;     ...
;             PG8_WAIT_V(8); PG8_WAIT_L(0); PG8_BAR; PG8_MMA(1, 0, At, B0); PG8_MMA(1, 1, At, B1); PG8_BAR; PG8_SCHED;
;             PG8_LDB(B0, 1, 0); PG8_LDB(B1, 1, 1); PG8_SCHED; PG8_LDA(At, 1, 0); PG8_STAGE(PG8_SA(0, 1), a2 + hstepA, voffA);
;             PG8_WAIT_V(8); PG8_WAIT_L(0); PG8_BAR; PG8_MMA(0, 0, At, B0); PG8_MMA(0, 1, At, B1); PG8_BAR; PG8_SCHED;
	s_setprio 1
	v_mfma_f32_16x16x32_bf16 v[60:63], v[152:155], v[184:187], v[60:63]
	v_mfma_f32_16x16x32_bf16 v[56:59], v[160:163], v[184:187], v[56:59]
	v_mfma_f32_16x16x32_bf16 v[52:55], v[152:155], v[192:195], v[52:55]
	v_mfma_f32_16x16x32_bf16 v[44:47], v[160:163], v[192:195], v[44:47]
	v_mfma_f32_16x16x32_bf16 v[36:39], v[152:155], v[200:203], v[36:39]
	v_mfma_f32_16x16x32_bf16 v[28:31], v[160:163], v[200:203], v[28:31]
	v_mfma_f32_16x16x32_bf16 v[20:23], v[152:155], v[210:213], v[20:23]
	v_mfma_f32_16x16x32_bf16 v[12:15], v[160:163], v[210:213], v[12:15]
	s_setprio 0
	s_setprio 1
	v_mfma_f32_16x16x32_bf16 v[60:63], v[156:159], v[188:191], v[60:63]
	v_mfma_f32_16x16x32_bf16 v[56:59], v[164:167], v[188:191], v[56:59]
	v_mfma_f32_16x16x32_bf16 v[52:55], v[156:159], v[196:199], v[52:55]
	v_mfma_f32_16x16x32_bf16 v[44:47], v[164:167], v[196:199], v[44:47]
	v_mfma_f32_16x16x32_bf16 v[36:39], v[156:159], v[204:207], v[36:39]
	v_mfma_f32_16x16x32_bf16 v[28:31], v[164:167], v[204:207], v[28:31]
	v_mfma_f32_16x16x32_bf16 v[20:23], v[156:159], v[214:217], v[20:23]
	v_mfma_f32_16x16x32_bf16 v[12:15], v[164:167], v[214:217], v[12:15]
	s_setprio 0
	s_setprio 1
	v_mfma_f32_16x16x32_bf16 v[48:51], v[168:171], v[184:187], v[48:51]
	v_mfma_f32_16x16x32_bf16 v[40:43], v[176:179], v[184:187], v[40:43]
	v_mfma_f32_16x16x32_bf16 v[32:35], v[168:171], v[192:195], v[32:35]
	v_mfma_f32_16x16x32_bf16 v[24:27], v[176:179], v[192:195], v[24:27]
	v_mfma_f32_16x16x32_bf16 v[16:19], v[168:171], v[200:203], v[16:19]
	v_mfma_f32_16x16x32_bf16 v[8:11], v[176:179], v[200:203], v[8:11]
	v_mfma_f32_16x16x32_bf16 v[4:7], v[168:171], v[210:213], v[4:7]
	v_mfma_f32_16x16x32_bf16 v[0:3], v[176:179], v[210:213], v[0:3]
	s_setprio 0
	s_setprio 1
	v_mfma_f32_16x16x32_bf16 v[48:51], v[172:175], v[188:191], v[48:51]
	v_mfma_f32_16x16x32_bf16 v[40:43], v[180:183], v[188:191], v[40:43]
	v_mfma_f32_16x16x32_bf16 v[32:35], v[172:175], v[196:199], v[32:35]
	v_mfma_f32_16x16x32_bf16 v[24:27], v[180:183], v[196:199], v[24:27]
	v_mfma_f32_16x16x32_bf16 v[16:19], v[172:175], v[204:207], v[16:19]
	v_mfma_f32_16x16x32_bf16 v[8:11], v[180:183], v[204:207], v[8:11]
	v_mfma_f32_16x16x32_bf16 v[4:7], v[172:175], v[214:217], v[4:7]
	v_mfma_f32_16x16x32_bf16 v[0:3], v[180:183], v[214:217], v[0:3]
	s_setprio 0
	s_barrier
	s_add_i32 s66, 0, 0x18000
	s_add_i32 s67, 0, 0x1c000
	v_add_u32_e32 v164, s66, v147
	v_add_u32_e32 v180, s67, v147
	ds_read_b128 v[152:155], v164
	ds_read_b128 v[156:159], v164 offset:1024
	ds_read_b128 v[160:163], v164 offset:2048
	ds_read_b128 v[164:167], v164 offset:3072
	ds_read_b128 v[168:171], v180
	ds_read_b128 v[172:175], v180 offset:1024
	ds_read_b128 v[176:179], v180 offset:2048
	ds_read_b128 v[180:183], v180 offset:3072
	s_add_u32 s46, s46, 0x40000
	s_addc_u32 s47, s47, 0
	s_mov_b32 m0, s37
	v_lshl_add_u64 v[224:225], s[46:47], 0, v[128:129]
	ds_read_b128 v[184:187], v151 offset:32768
	ds_read_b128 v[188:191], v151 offset:33792
	ds_read_b128 v[192:195], v151 offset:34816
	ds_read_b128 v[196:199], v151 offset:35840
	ds_read_b128 v[200:203], v151 offset:36864
	ds_read_b128 v[204:207], v151 offset:37888
	ds_read_b128 v[210:213], v151 offset:38912
	ds_read_b128 v[214:217], v151 offset:39936
	global_load_lds_dwordx4 v[224:225], off
	v_lshl_add_u64 v[224:225], s[46:47], 0, v[132:133]
	s_mov_b32 m0, s43
	s_nop 0
	global_load_lds_dwordx4 v[224:225], off
	s_waitcnt vmcnt(8) lgkmcnt(0)
	s_barrier
	s_setprio 1
	v_mfma_f32_16x16x32_bf16 v[124:127], v[152:155], v[184:187], v[124:127]
	v_mfma_f32_16x16x32_bf16 v[120:123], v[160:163], v[184:187], v[120:123]
	v_mfma_f32_16x16x32_bf16 v[116:119], v[152:155], v[192:195], v[116:119]
	v_mfma_f32_16x16x32_bf16 v[108:111], v[160:163], v[192:195], v[108:111]
	v_mfma_f32_16x16x32_bf16 v[100:103], v[152:155], v[200:203], v[100:103]
	v_mfma_f32_16x16x32_bf16 v[92:95], v[160:163], v[200:203], v[92:95]
	v_mfma_f32_16x16x32_bf16 v[84:87], v[152:155], v[210:213], v[84:87]
	v_mfma_f32_16x16x32_bf16 v[76:79], v[160:163], v[210:213], v[76:79]
	s_setprio 0
	s_setprio 1
	v_mfma_f32_16x16x32_bf16 v[124:127], v[156:159], v[188:191], v[124:127]
	v_mfma_f32_16x16x32_bf16 v[120:123], v[164:167], v[188:191], v[120:123]
	v_mfma_f32_16x16x32_bf16 v[116:119], v[156:159], v[196:199], v[116:119]
	v_mfma_f32_16x16x32_bf16 v[108:111], v[164:167], v[196:199], v[108:111]
	v_mfma_f32_16x16x32_bf16 v[100:103], v[156:159], v[204:207], v[100:103]
	v_mfma_f32_16x16x32_bf16 v[92:95], v[164:167], v[204:207], v[92:95]
	v_mfma_f32_16x16x32_bf16 v[84:87], v[156:159], v[214:217], v[84:87]
	v_mfma_f32_16x16x32_bf16 v[76:79], v[164:167], v[214:217], v[76:79]
	s_setprio 0
	s_setprio 1
	v_mfma_f32_16x16x32_bf16 v[112:115], v[168:171], v[184:187], v[112:115]
	v_mfma_f32_16x16x32_bf16 v[104:107], v[176:179], v[184:187], v[104:107]
	v_mfma_f32_16x16x32_bf16 v[96:99], v[168:171], v[192:195], v[96:99]
	v_mfma_f32_16x16x32_bf16 v[88:91], v[176:179], v[192:195], v[88:91]
	v_mfma_f32_16x16x32_bf16 v[80:83], v[168:171], v[200:203], v[80:83]
	v_mfma_f32_16x16x32_bf16 v[72:75], v[176:179], v[200:203], v[72:75]
	v_mfma_f32_16x16x32_bf16 v[68:71], v[168:171], v[210:213], v[68:71]
	v_mfma_f32_16x16x32_bf16 v[64:67], v[176:179], v[210:213], v[64:67]
	s_setprio 0
	s_setprio 1
	v_mfma_f32_16x16x32_bf16 v[112:115], v[172:175], v[188:191], v[112:115]
	v_mfma_f32_16x16x32_bf16 v[104:107], v[180:183], v[188:191], v[104:107]
	v_mfma_f32_16x16x32_bf16 v[96:99], v[172:175], v[196:199], v[96:99]
	v_mfma_f32_16x16x32_bf16 v[88:91], v[180:183], v[196:199], v[88:91]
	v_mfma_f32_16x16x32_bf16 v[80:83], v[172:175], v[204:207], v[80:83]
	v_mfma_f32_16x16x32_bf16 v[72:75], v[180:183], v[204:207], v[72:75]
	v_mfma_f32_16x16x32_bf16 v[68:71], v[172:175], v[214:217], v[68:71]
	v_mfma_f32_16x16x32_bf16 v[64:67], v[180:183], v[214:217], v[64:67]
	s_setprio 0
	s_barrier
; #define PG8_STAGE(bufoff, gbase, voff) do { _Pragma("unroll") for (int _i = 0; _i < 2; ++_i) \
;         __builtin_amdgcn_global_load_lds((const unsigned*)((const char*)(gbase) + (voff)[_i]), (LAS unsigned*)(lds + (bufoff) + ldsw + _i * 8192), 16, 0, 0); } while (0)
; #define PG8_LDA(dst, b, h) do { _Pragma("unroll") for (int m = 0; m < 4; ++m) _Pragma("unroll") for (int k = 0; k < 2; ++k) dst[m][k] = *(const LAS bf16x8*)(lds + PG8_SA(b, h) + aoff + m * 2048 + k * 1024); } while (0)
; #define PG8_MMA(ai, bj, At, Bt) do { __builtin_amdgcn_s_setprio(1); _Pragma("unroll") for (int m = 0; m < 4; ++m) _Pragma("unroll") for (int n = 0; n < 2; ++n) _Pragma("unroll") for (int k = 0; k < 2; ++k) \
;         acc[ai][bj][m][n] = __builtin_amdgcn_mfma_f32_16x16x32_bf16(Bt[n][k], At[m][k], acc[ai][bj][m][n], 0, 0, 0); __builtin_amdgcn_s_setprio(0); } while (0)
; #define PG8_WAIT_V(n) asm volatile("s_waitcnt vmcnt(" #n ")" ::: "memory")
; #define PG8_WAIT_L(n) asm volatile("s_waitcnt lgkmcnt(" #n ")" ::: "memory")
; #define PG8_BAR __builtin_amdgcn_s_barrier()
; #define PG8_SCHED __builtin_amdgcn_sched_barrier(0)
; template <class Epi, class Sched>
; __device__ __forceinline__ void gemm_phase(LAS unsigned char* lds, const Gemm g, const Sched& S, const Epi& E, const int wave_s) {
;     ...
;             PG8_LDA(At, 1, 1); PG8_STAGE(PG8_SB(1, 0), b3, voffB); PG8_STAGE(PG8_SB(1, 1), b3 + hstepB, voffB); PG8_STAGE(PG8_SA(1, 0), a3, voffA);
;             PG8_WAIT_V(8); PG8_WAIT_L(0); PG8_BAR; PG8_MMA(1, 0, At, B0); PG8_MMA(1, 1, At, B1); PG8_BAR; PG8_SCHED;
;         }
	s_add_i32 s46, s66, s81
	v_lshl_add_u64 v[144:145], v[144:145], 0, s[14:15]
	s_mov_b32 m0, s46
	ds_read_b128 v[184:187], v151 offset:49152
	ds_read_b128 v[188:191], v151 offset:50176
	ds_read_b128 v[192:195], v151 offset:51200
	ds_read_b128 v[196:199], v151 offset:52224
	ds_read_b128 v[200:203], v151 offset:53248
	ds_read_b128 v[204:207], v151 offset:54272
	ds_read_b128 v[210:213], v151 offset:55296
	ds_read_b128 v[214:217], v151 offset:56320
	global_load_lds_dwordx4 v[144:145], off
	s_add_i32 m0, s46, 0x2000
	s_add_u32 s4, s4, 0x40080
	v_lshl_add_u64 v[144:145], v[218:219], 0, s[14:15]
	s_addc_u32 s5, s5, 0
	s_add_i32 s46, s67, s81
	global_load_lds_dwordx4 v[144:145], off
	v_lshl_add_u64 v[144:145], s[4:5], 0, v[130:131]
	s_mov_b32 m0, s46
	s_nop 0
	global_load_lds_dwordx4 v[144:145], off
	v_lshl_add_u64 v[144:145], s[4:5], 0, v[134:135]
	s_add_i32 m0, s46, 0x2000
	s_nop 0
	global_load_lds_dwordx4 v[144:145], off
	v_lshl_add_u64 v[144:145], v[220:221], 0, s[14:15]
	s_mov_b32 m0, s49
	s_nop 0
	global_load_lds_dwordx4 v[144:145], off
	v_lshl_add_u64 v[144:145], v[222:223], 0, s[14:15]
	s_mov_b32 m0, s50
	s_nop 0
	global_load_lds_dwordx4 v[144:145], off
	s_waitcnt vmcnt(8) lgkmcnt(0)
	s_barrier
	s_setprio 1
	v_mfma_f32_16x16x32_bf16 v[60:63], v[152:155], v[184:187], v[60:63]
	v_mfma_f32_16x16x32_bf16 v[56:59], v[160:163], v[184:187], v[56:59]
	v_mfma_f32_16x16x32_bf16 v[52:55], v[152:155], v[192:195], v[52:55]
	v_mfma_f32_16x16x32_bf16 v[44:47], v[160:163], v[192:195], v[44:47]
	v_mfma_f32_16x16x32_bf16 v[36:39], v[152:155], v[200:203], v[36:39]
	v_mfma_f32_16x16x32_bf16 v[28:31], v[160:163], v[200:203], v[28:31]
	v_mfma_f32_16x16x32_bf16 v[20:23], v[152:155], v[210:213], v[20:23]
	v_mfma_f32_16x16x32_bf16 v[12:15], v[160:163], v[210:213], v[12:15]
	s_setprio 0
	s_setprio 1
	v_mfma_f32_16x16x32_bf16 v[60:63], v[156:159], v[188:191], v[60:63]
	v_mfma_f32_16x16x32_bf16 v[56:59], v[164:167], v[188:191], v[56:59]
	v_mfma_f32_16x16x32_bf16 v[52:55], v[156:159], v[196:199], v[52:55]
	v_mfma_f32_16x16x32_bf16 v[44:47], v[164:167], v[196:199], v[44:47]
	v_mfma_f32_16x16x32_bf16 v[36:39], v[156:159], v[204:207], v[36:39]
	v_mfma_f32_16x16x32_bf16 v[28:31], v[164:167], v[204:207], v[28:31]
	v_mfma_f32_16x16x32_bf16 v[20:23], v[156:159], v[214:217], v[20:23]
	v_mfma_f32_16x16x32_bf16 v[12:15], v[164:167], v[214:217], v[12:15]
	s_setprio 0
	s_setprio 1
	v_mfma_f32_16x16x32_bf16 v[48:51], v[168:171], v[184:187], v[48:51]
	v_mfma_f32_16x16x32_bf16 v[40:43], v[176:179], v[184:187], v[40:43]
	v_mfma_f32_16x16x32_bf16 v[32:35], v[168:171], v[192:195], v[32:35]
	v_mfma_f32_16x16x32_bf16 v[24:27], v[176:179], v[192:195], v[24:27]
	v_mfma_f32_16x16x32_bf16 v[16:19], v[168:171], v[200:203], v[16:19]
	v_mfma_f32_16x16x32_bf16 v[8:11], v[176:179], v[200:203], v[8:11]
	v_mfma_f32_16x16x32_bf16 v[4:7], v[168:171], v[210:213], v[4:7]
	v_mfma_f32_16x16x32_bf16 v[0:3], v[176:179], v[210:213], v[0:3]
	s_setprio 0
	s_setprio 1
	v_mfma_f32_16x16x32_bf16 v[48:51], v[172:175], v[188:191], v[48:51]
	v_mfma_f32_16x16x32_bf16 v[40:43], v[180:183], v[188:191], v[40:43]
	v_mfma_f32_16x16x32_bf16 v[32:35], v[172:175], v[196:199], v[32:35]
	v_mfma_f32_16x16x32_bf16 v[24:27], v[180:183], v[196:199], v[24:27]
	v_mfma_f32_16x16x32_bf16 v[16:19], v[172:175], v[204:207], v[16:19]
	v_mfma_f32_16x16x32_bf16 v[8:11], v[180:183], v[204:207], v[8:11]
	v_mfma_f32_16x16x32_bf16 v[4:7], v[172:175], v[214:217], v[4:7]
	v_mfma_f32_16x16x32_bf16 v[0:3], v[180:183], v[214:217], v[0:3]
	s_setprio 0
	s_barrier
	s_add_i32 s65, s65, 2
	s_add_u32 s44, s44, 0x100
	s_addc_u32 s45, s45, 0
	s_add_u32 s63, s63, 0x100
	s_addc_u32 s64, s64, 0
	s_cmp_gt_u32 s65, 13
	s_cbranch_scc0 .LBB0_125
	s_and_b64 vcc, exec, s[16:17]
	s_cbranch_vccz .LBB0_128
	s_barrier

; #define PG8_STAGE(bufoff, gbase, voff) do { _Pragma("unroll") for (int _i = 0; _i < 2; ++_i) \
;         __builtin_amdgcn_global_load_lds((const unsigned*)((const char*)(gbase) + (voff)[_i]), (LAS unsigned*)(lds + (bufoff) + ldsw + _i * 8192), 16, 0, 0); } while (0)
; #define PG8_LDA(dst, b, h) do { _Pragma("unroll") for (int m = 0; m < 4; ++m) _Pragma("unroll") for (int k = 0; k < 2; ++k) dst[m][k] = *(const LAS bf16x8*)(lds + PG8_SA(b, h) + aoff + m * 2048 + k * 1024); } while (0)
; #define PG8_LDB(dst, b, h) do { _Pragma("unroll") for (int n = 0; n < 2; ++n) _Pragma("unroll") for (int k = 0; k < 2; ++k) dst[n][k] = *(const LAS bf16x8*)(lds + PG8_SB(b, h) + boff + n * 2048 + k * 1024); } while (0)
; #define PG8_MMA(ai, bj, At, Bt) do { __builtin_amdgcn_s_setprio(1); _Pragma("unroll") for (int m = 0; m < 4; ++m) _Pragma("unroll") for (int n = 0; n < 2; ++n) _Pragma("unroll") for (int k = 0; k < 2; ++k) \
;         acc[ai][bj][m][n] = __builtin_amdgcn_mfma_f32_16x16x32_bf16(Bt[n][k], At[m][k], acc[ai][bj][m][n], 0, 0, 0); __builtin_amdgcn_s_setprio(0); } while (0)
; #define PG8_WAIT_V(n) asm volatile("s_waitcnt vmcnt(" #n ")" ::: "memory")
; #define PG8_WAIT_L(n) asm volatile("s_waitcnt lgkmcnt(" #n ")" ::: "memory")
; #define PG8_BAR __builtin_amdgcn_s_barrier()
; #define PG8_SCHED __builtin_amdgcn_sched_barrier(0)
; template <class Epi, class Sched>
; __device__ __forceinline__ void gemm_phase(LAS unsigned char* lds, const Gemm g, const Sched& S, const Epi& E, const int wave_s) {
;     ...
;             const bool last = (t == nt - 2);
;             const char* a1 = cA + (size_t)(t + 1) * kstep;
;             const char* a2 = last ? nA : cA + (size_t)(t + 2) * kstep; const char* b2 = last ? nB : cB + (size_t)(t + 2) * kstep;
;             const char* a3 = a2 + kstep; const char* b3 = b2 + kstep;
;             PG8_LDB(B0, 0, 0); PG8_LDB(B1, 0, 1); PG8_SCHED; PG8_LDA(At, 0, 0); PG8_STAGE(PG8_SA(1, 1), a1 + hstepA, voffA);
;             PG8_WAIT_V(8); PG8_WAIT_L(0); PG8_BAR; PG8_MMA(0, 0, At, B0); PG8_MMA(0, 1, At, B1); PG8_BAR; PG8_SCHED;
;             PG8_LDA(At, 0, 1); PG8_STAGE(PG8_SB(0, 0), b2, voffB); PG8_STAGE(PG8_SB(0, 1), b2 + hstepB, voffB); PG8_STAGE(PG8_SA(0, 0), a2, voffA);
;             PG8_WAIT_V(8); PG8_WAIT_L(0); PG8_BAR; PG8_MMA(1, 0, At, B0); PG8_MMA(1, 1, At, B1); PG8_BAR; PG8_SCHED;
.LBB0_194:
	ds_read_b128 v[144:147], v151
	ds_read_b128 v[154:157], v151 offset:1024
	ds_read_b128 v[158:161], v151 offset:2048
	ds_read_b128 v[162:165], v151 offset:3072
	ds_read_b128 v[166:169], v152
	ds_read_b128 v[170:173], v152 offset:1024
	ds_read_b128 v[174:177], v152 offset:2048
	ds_read_b128 v[178:181], v152 offset:3072
	s_add_u32 s4, s24, 0xfffc0080
	s_addc_u32 s5, s25, -1
	s_cmp_eq_u32 s54, 12
	s_cselect_b32 s27, s19, s5
	s_cselect_b32 s26, s50, s4
	s_cselect_b32 s5, s17, s53
	s_cselect_b32 s4, s51, s52
	v_lshl_add_u64 v[206:207], s[24:25], 0, v[136:137]
	s_add_i32 m0, s30, 0xc000
	ds_read_b128 v[182:185], v153
	ds_read_b128 v[186:189], v153 offset:1024
	ds_read_b128 v[190:193], v153 offset:2048
	ds_read_b128 v[194:197], v153 offset:3072
	ds_read_b128 v[198:201], v153 offset:4096
	ds_read_b128 v[202:205], v153 offset:5120
	ds_read_b128 v[210:213], v153 offset:6144
	ds_read_b128 v[214:217], v153 offset:7168
	global_load_lds_dwordx4 v[206:207], off
	v_lshl_add_u64 v[206:207], s[24:25], 0, v[138:139]
	s_add_i32 m0, s30, 0xe000
	s_nop 0
	global_load_lds_dwordx4 v[206:207], off
	s_waitcnt vmcnt(8) lgkmcnt(0)
	s_barrier
	s_setprio 1
	v_mfma_f32_16x16x32_bf16 v[124:127], v[144:147], v[182:185], v[124:127]
	v_mfma_f32_16x16x32_bf16 v[120:123], v[158:161], v[182:185], v[120:123]
	v_mfma_f32_16x16x32_bf16 v[116:119], v[144:147], v[190:193], v[116:119]
	v_mfma_f32_16x16x32_bf16 v[108:111], v[158:161], v[190:193], v[108:111]
	v_mfma_f32_16x16x32_bf16 v[100:103], v[144:147], v[198:201], v[100:103]
	v_mfma_f32_16x16x32_bf16 v[92:95], v[158:161], v[198:201], v[92:95]
	v_mfma_f32_16x16x32_bf16 v[84:87], v[144:147], v[210:213], v[84:87]
	v_mfma_f32_16x16x32_bf16 v[76:79], v[158:161], v[210:213], v[76:79]
	s_setprio 0
	s_setprio 1
	v_mfma_f32_16x16x32_bf16 v[124:127], v[154:157], v[186:189], v[124:127]
	v_mfma_f32_16x16x32_bf16 v[120:123], v[162:165], v[186:189], v[120:123]
	v_mfma_f32_16x16x32_bf16 v[116:119], v[154:157], v[194:197], v[116:119]
	v_mfma_f32_16x16x32_bf16 v[108:111], v[162:165], v[194:197], v[108:111]
	v_mfma_f32_16x16x32_bf16 v[100:103], v[154:157], v[202:205], v[100:103]
	v_mfma_f32_16x16x32_bf16 v[92:95], v[162:165], v[202:205], v[92:95]
	v_mfma_f32_16x16x32_bf16 v[84:87], v[154:157], v[214:217], v[84:87]
	v_mfma_f32_16x16x32_bf16 v[76:79], v[162:165], v[214:217], v[76:79]
	s_setprio 0
	s_setprio 1
	v_mfma_f32_16x16x32_bf16 v[112:115], v[166:169], v[182:185], v[112:115]
	v_mfma_f32_16x16x32_bf16 v[104:107], v[174:177], v[182:185], v[104:107]
	v_mfma_f32_16x16x32_bf16 v[96:99], v[166:169], v[190:193], v[96:99]
	v_mfma_f32_16x16x32_bf16 v[88:91], v[174:177], v[190:193], v[88:91]
	v_mfma_f32_16x16x32_bf16 v[80:83], v[166:169], v[198:201], v[80:83]
	v_mfma_f32_16x16x32_bf16 v[72:75], v[174:177], v[198:201], v[72:75]
	v_mfma_f32_16x16x32_bf16 v[68:71], v[166:169], v[210:213], v[68:71]
	v_mfma_f32_16x16x32_bf16 v[64:67], v[174:177], v[210:213], v[64:67]
	s_setprio 0
	s_setprio 1
	v_mfma_f32_16x16x32_bf16 v[112:115], v[170:173], v[186:189], v[112:115]
	v_mfma_f32_16x16x32_bf16 v[104:107], v[178:181], v[186:189], v[104:107]
	v_mfma_f32_16x16x32_bf16 v[96:99], v[170:173], v[194:197], v[96:99]
	v_mfma_f32_16x16x32_bf16 v[88:91], v[178:181], v[194:197], v[88:91]
	v_mfma_f32_16x16x32_bf16 v[80:83], v[170:173], v[202:205], v[80:83]
	v_mfma_f32_16x16x32_bf16 v[72:75], v[178:181], v[202:205], v[72:75]
	v_mfma_f32_16x16x32_bf16 v[68:71], v[170:173], v[214:217], v[68:71]
	v_mfma_f32_16x16x32_bf16 v[64:67], v[178:181], v[214:217], v[64:67]
	s_setprio 0
	s_barrier
	s_add_i32 s55, s45, s81
	v_lshl_add_u64 v[206:207], s[4:5], 0, v[132:133]
	s_mov_b32 m0, s55
	ds_read_b128 v[182:185], v153 offset:16384
	ds_read_b128 v[186:189], v153 offset:17408
	ds_read_b128 v[190:193], v153 offset:18432
	ds_read_b128 v[194:197], v153 offset:19456
	ds_read_b128 v[198:201], v153 offset:20480
	ds_read_b128 v[202:205], v153 offset:21504
	ds_read_b128 v[210:213], v153 offset:22528
	ds_read_b128 v[214:217], v153 offset:23552
	global_load_lds_dwordx4 v[206:207], off
	s_add_i32 m0, s55, 0x2000
	s_add_u32 s58, s4, 0x40000
	v_lshl_add_u64 v[218:219], s[4:5], 0, v[128:129]
	s_addc_u32 s59, s5, 0
	s_add_i32 s55, s46, s81
	global_load_lds_dwordx4 v[218:219], off
	v_lshl_add_u64 v[220:221], s[58:59], 0, v[132:133]
	s_mov_b32 m0, s55
	v_lshl_add_u64 v[222:223], s[26:27], 0, v[130:131]
	global_load_lds_dwordx4 v[220:221], off
	v_lshl_add_u64 v[220:221], s[58:59], 0, v[128:129]
	s_add_i32 m0, s55, 0x2000
	s_nop 0
	global_load_lds_dwordx4 v[220:221], off
	v_lshl_add_u64 v[220:221], s[26:27], 0, v[134:135]
	s_mov_b32 m0, s30
	s_nop 0
	global_load_lds_dwordx4 v[220:221], off
	s_mov_b32 m0, s31
	s_nop 0
	global_load_lds_dwordx4 v[222:223], off
	s_waitcnt vmcnt(8) lgkmcnt(0)
	s_barrier
; #define PG8_STAGE(bufoff, gbase, voff) do { _Pragma("unroll") for (int _i = 0; _i < 2; ++_i) \
;         __builtin_amdgcn_global_load_lds((const unsigned*)((const char*)(gbase) + (voff)[_i]), (LAS unsigned*)(lds + (bufoff) + ldsw + _i * 8192), 16, 0, 0); } while (0)
; #define PG8_LDA(dst, b, h) do { _Pragma("unroll") for (int m = 0; m < 4; ++m) _Pragma("unroll") for (int k = 0; k < 2; ++k) dst[m][k] = *(const LAS bf16x8*)(lds + PG8_SA(b, h) + aoff + m * 2048 + k * 1024); } while (0)
; #define PG8_LDB(dst, b, h) do { _Pragma("unroll") for (int n = 0; n < 2; ++n) _Pragma("unroll") for (int k = 0; k < 2; ++k) dst[n][k] = *(const LAS bf16x8*)(lds + PG8_SB(b, h) + boff + n * 2048 + k * 1024); } while (0)
; #define PG8_MMA(ai, bj, At, Bt) do { __builtin_amdgcn_s_setprio(1); _Pragma("unroll") for (int m = 0; m < 4; ++m) _Pragma("unroll") for (int n = 0; n < 2; ++n) _Pragma("unroll") for (int k = 0; k < 2; ++k) \
;         acc[ai][bj][m][n] = __builtin_amdgcn_mfma_f32_16x16x32_bf16(Bt[n][k], At[m][k], acc[ai][bj][m][n], 0, 0, 0); __builtin_amdgcn_s_setprio(0); } while (0)
; #define PG8_WAIT_V(n) asm volatile("s_waitcnt vmcnt(" #n ")" ::: "memory")
; #define PG8_WAIT_L(n) asm volatile("s_waitcnt lgkmcnt(" #n ")" ::: "memory")
; #define PG8_BAR __builtin_amdgcn_s_barrier()
; #define PG8_SCHED __builtin_amdgcn_sched_barrier(0)
; template <class Epi, class Sched>
; __device__ __forceinline__ void gemm_phase(LAS unsigned char* lds, const Gemm g, const Sched& S, const Epi& E, const int wave_s) {
;     ...
;             PG8_WAIT_V(8); PG8_WAIT_L(0); PG8_BAR; PG8_MMA(1, 0, At, B0); PG8_MMA(1, 1, At, B1); PG8_BAR; PG8_SCHED;
;             PG8_LDB(B0, 1, 0); PG8_LDB(B1, 1, 1); PG8_SCHED; PG8_LDA(At, 1, 0); PG8_STAGE(PG8_SA(0, 1), a2 + hstepA, voffA);
;             PG8_WAIT_V(8); PG8_WAIT_L(0); PG8_BAR; PG8_MMA(0, 0, At, B0); PG8_MMA(0, 1, At, B1); PG8_BAR; PG8_SCHED;
	s_setprio 1
	v_mfma_f32_16x16x32_bf16 v[60:63], v[144:147], v[182:185], v[60:63]
	v_mfma_f32_16x16x32_bf16 v[56:59], v[158:161], v[182:185], v[56:59]
	v_mfma_f32_16x16x32_bf16 v[52:55], v[144:147], v[190:193], v[52:55]
	v_mfma_f32_16x16x32_bf16 v[44:47], v[158:161], v[190:193], v[44:47]
	v_mfma_f32_16x16x32_bf16 v[36:39], v[144:147], v[198:201], v[36:39]
	v_mfma_f32_16x16x32_bf16 v[28:31], v[158:161], v[198:201], v[28:31]
	v_mfma_f32_16x16x32_bf16 v[20:23], v[144:147], v[210:213], v[20:23]
	v_mfma_f32_16x16x32_bf16 v[12:15], v[158:161], v[210:213], v[12:15]
	s_setprio 0
	s_setprio 1
	v_mfma_f32_16x16x32_bf16 v[60:63], v[154:157], v[186:189], v[60:63]
	v_mfma_f32_16x16x32_bf16 v[56:59], v[162:165], v[186:189], v[56:59]
	v_mfma_f32_16x16x32_bf16 v[52:55], v[154:157], v[194:197], v[52:55]
	v_mfma_f32_16x16x32_bf16 v[44:47], v[162:165], v[194:197], v[44:47]
	v_mfma_f32_16x16x32_bf16 v[36:39], v[154:157], v[202:205], v[36:39]
	v_mfma_f32_16x16x32_bf16 v[28:31], v[162:165], v[202:205], v[28:31]
	v_mfma_f32_16x16x32_bf16 v[20:23], v[154:157], v[214:217], v[20:23]
	v_mfma_f32_16x16x32_bf16 v[12:15], v[162:165], v[214:217], v[12:15]
	s_setprio 0
	s_setprio 1
	v_mfma_f32_16x16x32_bf16 v[48:51], v[166:169], v[182:185], v[48:51]
	v_mfma_f32_16x16x32_bf16 v[40:43], v[174:177], v[182:185], v[40:43]
	v_mfma_f32_16x16x32_bf16 v[32:35], v[166:169], v[190:193], v[32:35]
	v_mfma_f32_16x16x32_bf16 v[24:27], v[174:177], v[190:193], v[24:27]
	v_mfma_f32_16x16x32_bf16 v[16:19], v[166:169], v[198:201], v[16:19]
	v_mfma_f32_16x16x32_bf16 v[8:11], v[174:177], v[198:201], v[8:11]
	v_mfma_f32_16x16x32_bf16 v[4:7], v[166:169], v[210:213], v[4:7]
	v_mfma_f32_16x16x32_bf16 v[0:3], v[174:177], v[210:213], v[0:3]
	s_setprio 0
	s_setprio 1
	v_mfma_f32_16x16x32_bf16 v[48:51], v[170:173], v[186:189], v[48:51]
	v_mfma_f32_16x16x32_bf16 v[40:43], v[178:181], v[186:189], v[40:43]
	v_mfma_f32_16x16x32_bf16 v[32:35], v[170:173], v[194:197], v[32:35]
	v_mfma_f32_16x16x32_bf16 v[24:27], v[178:181], v[194:197], v[24:27]
	v_mfma_f32_16x16x32_bf16 v[16:19], v[170:173], v[202:205], v[16:19]
	v_mfma_f32_16x16x32_bf16 v[8:11], v[178:181], v[202:205], v[8:11]
	v_mfma_f32_16x16x32_bf16 v[4:7], v[170:173], v[214:217], v[4:7]
	v_mfma_f32_16x16x32_bf16 v[0:3], v[178:181], v[214:217], v[0:3]
	s_setprio 0
	s_barrier
	s_add_i32 s55, 0, 0x18000
	s_add_i32 s57, 0, 0x1c000
	v_add_u32_e32 v162, s55, v149
	v_add_u32_e32 v178, s57, v149
	ds_read_b128 v[144:147], v162
	ds_read_b128 v[154:157], v162 offset:1024
	ds_read_b128 v[158:161], v162 offset:2048
	ds_read_b128 v[162:165], v162 offset:3072
	ds_read_b128 v[166:169], v178
	ds_read_b128 v[170:173], v178 offset:1024
	ds_read_b128 v[174:177], v178 offset:2048
	ds_read_b128 v[178:181], v178 offset:3072
	s_add_u32 s26, s26, 0x40000
	s_addc_u32 s27, s27, 0
	s_mov_b32 m0, s33
	v_lshl_add_u64 v[224:225], s[26:27], 0, v[134:135]
	ds_read_b128 v[182:185], v153 offset:32768
	ds_read_b128 v[186:189], v153 offset:33792
	ds_read_b128 v[190:193], v153 offset:34816
	ds_read_b128 v[194:197], v153 offset:35840
	ds_read_b128 v[198:201], v153 offset:36864
	ds_read_b128 v[202:205], v153 offset:37888
	ds_read_b128 v[210:213], v153 offset:38912
	ds_read_b128 v[214:217], v153 offset:39936
	global_load_lds_dwordx4 v[224:225], off
	v_lshl_add_u64 v[224:225], s[26:27], 0, v[130:131]
	s_mov_b32 m0, s35
	s_nop 0
	global_load_lds_dwordx4 v[224:225], off
	s_waitcnt vmcnt(8) lgkmcnt(0)
	s_barrier
	s_setprio 1
	v_mfma_f32_16x16x32_bf16 v[124:127], v[144:147], v[182:185], v[124:127]
	v_mfma_f32_16x16x32_bf16 v[120:123], v[158:161], v[182:185], v[120:123]
	v_mfma_f32_16x16x32_bf16 v[116:119], v[144:147], v[190:193], v[116:119]
	v_mfma_f32_16x16x32_bf16 v[108:111], v[158:161], v[190:193], v[108:111]
	v_mfma_f32_16x16x32_bf16 v[100:103], v[144:147], v[198:201], v[100:103]
	v_mfma_f32_16x16x32_bf16 v[92:95], v[158:161], v[198:201], v[92:95]
	v_mfma_f32_16x16x32_bf16 v[84:87], v[144:147], v[210:213], v[84:87]
	v_mfma_f32_16x16x32_bf16 v[76:79], v[158:161], v[210:213], v[76:79]
	s_setprio 0
	s_setprio 1
	v_mfma_f32_16x16x32_bf16 v[124:127], v[154:157], v[186:189], v[124:127]
	v_mfma_f32_16x16x32_bf16 v[120:123], v[162:165], v[186:189], v[120:123]
	v_mfma_f32_16x16x32_bf16 v[116:119], v[154:157], v[194:197], v[116:119]
	v_mfma_f32_16x16x32_bf16 v[108:111], v[162:165], v[194:197], v[108:111]
	v_mfma_f32_16x16x32_bf16 v[100:103], v[154:157], v[202:205], v[100:103]
	v_mfma_f32_16x16x32_bf16 v[92:95], v[162:165], v[202:205], v[92:95]
	v_mfma_f32_16x16x32_bf16 v[84:87], v[154:157], v[214:217], v[84:87]
	v_mfma_f32_16x16x32_bf16 v[76:79], v[162:165], v[214:217], v[76:79]
	s_setprio 0
	s_setprio 1
	v_mfma_f32_16x16x32_bf16 v[112:115], v[166:169], v[182:185], v[112:115]
	v_mfma_f32_16x16x32_bf16 v[104:107], v[174:177], v[182:185], v[104:107]
	v_mfma_f32_16x16x32_bf16 v[96:99], v[166:169], v[190:193], v[96:99]
	v_mfma_f32_16x16x32_bf16 v[88:91], v[174:177], v[190:193], v[88:91]
	v_mfma_f32_16x16x32_bf16 v[80:83], v[166:169], v[198:201], v[80:83]
	v_mfma_f32_16x16x32_bf16 v[72:75], v[174:177], v[198:201], v[72:75]
	v_mfma_f32_16x16x32_bf16 v[68:71], v[166:169], v[210:213], v[68:71]
	v_mfma_f32_16x16x32_bf16 v[64:67], v[174:177], v[210:213], v[64:67]
	s_setprio 0
	s_setprio 1
	v_mfma_f32_16x16x32_bf16 v[112:115], v[170:173], v[186:189], v[112:115]
	v_mfma_f32_16x16x32_bf16 v[104:107], v[178:181], v[186:189], v[104:107]
	v_mfma_f32_16x16x32_bf16 v[96:99], v[170:173], v[194:197], v[96:99]
	v_mfma_f32_16x16x32_bf16 v[88:91], v[178:181], v[194:197], v[88:91]
	v_mfma_f32_16x16x32_bf16 v[80:83], v[170:173], v[202:205], v[80:83]
	v_mfma_f32_16x16x32_bf16 v[72:75], v[178:181], v[202:205], v[72:75]
	v_mfma_f32_16x16x32_bf16 v[68:71], v[170:173], v[214:217], v[68:71]
	v_mfma_f32_16x16x32_bf16 v[64:67], v[178:181], v[214:217], v[64:67]
	s_setprio 0
	s_barrier
; #define PG8_STAGE(bufoff, gbase, voff) do { _Pragma("unroll") for (int _i = 0; _i < 2; ++_i) \
;         __builtin_amdgcn_global_load_lds((const unsigned*)((const char*)(gbase) + (voff)[_i]), (LAS unsigned*)(lds + (bufoff) + ldsw + _i * 8192), 16, 0, 0); } while (0)
; #define PG8_LDA(dst, b, h) do { _Pragma("unroll") for (int m = 0; m < 4; ++m) _Pragma("unroll") for (int k = 0; k < 2; ++k) dst[m][k] = *(const LAS bf16x8*)(lds + PG8_SA(b, h) + aoff + m * 2048 + k * 1024); } while (0)
; #define PG8_MMA(ai, bj, At, Bt) do { __builtin_amdgcn_s_setprio(1); _Pragma("unroll") for (int m = 0; m < 4; ++m) _Pragma("unroll") for (int n = 0; n < 2; ++n) _Pragma("unroll") for (int k = 0; k < 2; ++k) \
;         acc[ai][bj][m][n] = __builtin_amdgcn_mfma_f32_16x16x32_bf16(Bt[n][k], At[m][k], acc[ai][bj][m][n], 0, 0, 0); __builtin_amdgcn_s_setprio(0); } while (0)
; #define PG8_WAIT_V(n) asm volatile("s_waitcnt vmcnt(" #n ")" ::: "memory")
; #define PG8_WAIT_L(n) asm volatile("s_waitcnt lgkmcnt(" #n ")" ::: "memory")
; #define PG8_BAR __builtin_amdgcn_s_barrier()
; #define PG8_SCHED __builtin_amdgcn_sched_barrier(0)
; template <class Epi, class Sched>
; __device__ __forceinline__ void gemm_phase(LAS unsigned char* lds, const Gemm g, const Sched& S, const Epi& E, const int wave_s) {
;     ...
;             PG8_LDA(At, 1, 1); PG8_STAGE(PG8_SB(1, 0), b3, voffB); PG8_STAGE(PG8_SB(1, 1), b3 + hstepB, voffB); PG8_STAGE(PG8_SA(1, 0), a3, voffA);
;             PG8_WAIT_V(8); PG8_WAIT_L(0); PG8_BAR; PG8_MMA(1, 0, At, B0); PG8_MMA(1, 1, At, B1); PG8_BAR; PG8_SCHED;
;         }
	s_add_i32 s26, s55, s81
	v_lshl_add_u64 v[206:207], v[206:207], 0, s[12:13]
	s_mov_b32 m0, s26
	ds_read_b128 v[182:185], v153 offset:49152
	ds_read_b128 v[186:189], v153 offset:50176
	ds_read_b128 v[190:193], v153 offset:51200
	ds_read_b128 v[194:197], v153 offset:52224
	ds_read_b128 v[198:201], v153 offset:53248
	ds_read_b128 v[202:205], v153 offset:54272
	ds_read_b128 v[210:213], v153 offset:55296
	ds_read_b128 v[214:217], v153 offset:56320
	global_load_lds_dwordx4 v[206:207], off
	s_add_i32 m0, s26, 0x2000
	s_add_u32 s4, s4, 0x40080
	v_lshl_add_u64 v[206:207], v[218:219], 0, s[12:13]
	s_addc_u32 s5, s5, 0
	s_add_i32 s26, s57, s81
	global_load_lds_dwordx4 v[206:207], off
	v_lshl_add_u64 v[206:207], s[4:5], 0, v[132:133]
	s_mov_b32 m0, s26
	s_nop 0
	global_load_lds_dwordx4 v[206:207], off
	v_lshl_add_u64 v[206:207], s[4:5], 0, v[128:129]
	s_add_i32 m0, s26, 0x2000
	s_nop 0
	global_load_lds_dwordx4 v[206:207], off
	v_lshl_add_u64 v[206:207], v[220:221], 0, s[12:13]
	s_mov_b32 m0, s41
	s_nop 0
	global_load_lds_dwordx4 v[206:207], off
	v_lshl_add_u64 v[206:207], v[222:223], 0, s[12:13]
	s_mov_b32 m0, s42
	s_nop 0
	global_load_lds_dwordx4 v[206:207], off
	s_waitcnt vmcnt(8) lgkmcnt(0)
	s_barrier
	s_setprio 1
	v_mfma_f32_16x16x32_bf16 v[60:63], v[144:147], v[182:185], v[60:63]
	v_mfma_f32_16x16x32_bf16 v[56:59], v[158:161], v[182:185], v[56:59]
	v_mfma_f32_16x16x32_bf16 v[52:55], v[144:147], v[190:193], v[52:55]
	v_mfma_f32_16x16x32_bf16 v[44:47], v[158:161], v[190:193], v[44:47]
	v_mfma_f32_16x16x32_bf16 v[36:39], v[144:147], v[198:201], v[36:39]
	v_mfma_f32_16x16x32_bf16 v[28:31], v[158:161], v[198:201], v[28:31]
	v_mfma_f32_16x16x32_bf16 v[20:23], v[144:147], v[210:213], v[20:23]
	v_mfma_f32_16x16x32_bf16 v[12:15], v[158:161], v[210:213], v[12:15]
	s_setprio 0
	s_setprio 1
	v_mfma_f32_16x16x32_bf16 v[60:63], v[154:157], v[186:189], v[60:63]
	v_mfma_f32_16x16x32_bf16 v[56:59], v[162:165], v[186:189], v[56:59]
	v_mfma_f32_16x16x32_bf16 v[52:55], v[154:157], v[194:197], v[52:55]
	v_mfma_f32_16x16x32_bf16 v[44:47], v[162:165], v[194:197], v[44:47]
	v_mfma_f32_16x16x32_bf16 v[36:39], v[154:157], v[202:205], v[36:39]
	v_mfma_f32_16x16x32_bf16 v[28:31], v[162:165], v[202:205], v[28:31]
	v_mfma_f32_16x16x32_bf16 v[20:23], v[154:157], v[214:217], v[20:23]
	v_mfma_f32_16x16x32_bf16 v[12:15], v[162:165], v[214:217], v[12:15]
	s_setprio 0
	s_setprio 1
	v_mfma_f32_16x16x32_bf16 v[48:51], v[166:169], v[182:185], v[48:51]
	v_mfma_f32_16x16x32_bf16 v[40:43], v[174:177], v[182:185], v[40:43]
	v_mfma_f32_16x16x32_bf16 v[32:35], v[166:169], v[190:193], v[32:35]
	v_mfma_f32_16x16x32_bf16 v[24:27], v[174:177], v[190:193], v[24:27]
	v_mfma_f32_16x16x32_bf16 v[16:19], v[166:169], v[198:201], v[16:19]
	v_mfma_f32_16x16x32_bf16 v[8:11], v[174:177], v[198:201], v[8:11]
	v_mfma_f32_16x16x32_bf16 v[4:7], v[166:169], v[210:213], v[4:7]
	v_mfma_f32_16x16x32_bf16 v[0:3], v[174:177], v[210:213], v[0:3]
	s_setprio 0
	s_setprio 1
	v_mfma_f32_16x16x32_bf16 v[48:51], v[170:173], v[186:189], v[48:51]
	v_mfma_f32_16x16x32_bf16 v[40:43], v[178:181], v[186:189], v[40:43]
	v_mfma_f32_16x16x32_bf16 v[32:35], v[170:173], v[194:197], v[32:35]
	v_mfma_f32_16x16x32_bf16 v[24:27], v[178:181], v[194:197], v[24:27]
	v_mfma_f32_16x16x32_bf16 v[16:19], v[170:173], v[202:205], v[16:19]
	v_mfma_f32_16x16x32_bf16 v[8:11], v[178:181], v[202:205], v[8:11]
	v_mfma_f32_16x16x32_bf16 v[4:7], v[170:173], v[214:217], v[4:7]
	v_mfma_f32_16x16x32_bf16 v[0:3], v[178:181], v[214:217], v[0:3]
	s_setprio 0
	s_barrier
	s_add_i32 s54, s54, 2
	s_add_u32 s24, s24, 0x100
	s_addc_u32 s25, s25, 0
	s_add_u32 s52, s52, 0x100
	s_addc_u32 s53, s53, 0
	s_cmp_gt_u32 s54, 13
	s_cbranch_scc0 .LBB0_194
	s_and_b64 vcc, exec, s[14:15]
	s_cbranch_vccz .LBB0_197
	s_barrier

; #define PG8_STAGE(bufoff, gbase, voff) do { _Pragma("unroll") for (int _i = 0; _i < 2; ++_i) \
;         __builtin_amdgcn_global_load_lds((const unsigned*)((const char*)(gbase) + (voff)[_i]), (LAS unsigned*)(lds + (bufoff) + ldsw + _i * 8192), 16, 0, 0); } while (0)
; #define PG8_LDA(dst, b, h) do { _Pragma("unroll") for (int m = 0; m < 4; ++m) _Pragma("unroll") for (int k = 0; k < 2; ++k) dst[m][k] = *(const LAS bf16x8*)(lds + PG8_SA(b, h) + aoff + m * 2048 + k * 1024); } while (0)
; #define PG8_LDB(dst, b, h) do { _Pragma("unroll") for (int n = 0; n < 2; ++n) _Pragma("unroll") for (int k = 0; k < 2; ++k) dst[n][k] = *(const LAS bf16x8*)(lds + PG8_SB(b, h) + boff + n * 2048 + k * 1024); } while (0)
; #define PG8_MMA(ai, bj, At, Bt) do { __builtin_amdgcn_s_setprio(1); _Pragma("unroll") for (int m = 0; m < 4; ++m) _Pragma("unroll") for (int n = 0; n < 2; ++n) _Pragma("unroll") for (int k = 0; k < 2; ++k) \
;         acc[ai][bj][m][n] = __builtin_amdgcn_mfma_f32_16x16x32_bf16(Bt[n][k], At[m][k], acc[ai][bj][m][n], 0, 0, 0); __builtin_amdgcn_s_setprio(0); } while (0)
; #define PG8_WAIT_V(n) asm volatile("s_waitcnt vmcnt(" #n ")" ::: "memory")
; #define PG8_WAIT_L(n) asm volatile("s_waitcnt lgkmcnt(" #n ")" ::: "memory")
; #define PG8_BAR __builtin_amdgcn_s_barrier()
; #define PG8_SCHED __builtin_amdgcn_sched_barrier(0)
; template <class Epi, class Sched>
; __device__ __forceinline__ void gemm_phase(LAS unsigned char* lds, const Gemm g, const Sched& S, const Epi& E, const int wave_s) {
;     ...
;             const bool last = (t == nt - 2);
;             const char* a1 = cA + (size_t)(t + 1) * kstep;
;             const char* a2 = last ? nA : cA + (size_t)(t + 2) * kstep; const char* b2 = last ? nB : cB + (size_t)(t + 2) * kstep;
;             const char* a3 = a2 + kstep; const char* b3 = b2 + kstep;
;             PG8_LDB(B0, 0, 0); PG8_LDB(B1, 0, 1); PG8_SCHED; PG8_LDA(At, 0, 0); PG8_STAGE(PG8_SA(1, 1), a1 + hstepA, voffA);
;             PG8_WAIT_V(8); PG8_WAIT_L(0); PG8_BAR; PG8_MMA(0, 0, At, B0); PG8_MMA(0, 1, At, B1); PG8_BAR; PG8_SCHED;
;             PG8_LDA(At, 0, 1); PG8_STAGE(PG8_SB(0, 0), b2, voffB); PG8_STAGE(PG8_SB(0, 1), b2 + hstepB, voffB); PG8_STAGE(PG8_SA(0, 0), a2, voffA);
;             PG8_WAIT_V(8); PG8_WAIT_L(0); PG8_BAR; PG8_MMA(1, 0, At, B0); PG8_MMA(1, 1, At, B1); PG8_BAR; PG8_SCHED;
.LBB0_375:
	ds_read_b128 v[158:161], v155
	ds_read_b128 v[162:165], v155 offset:1024
	ds_read_b128 v[166:169], v155 offset:2048
	ds_read_b128 v[170:173], v155 offset:3072
	ds_read_b128 v[174:177], v156
	ds_read_b128 v[178:181], v156 offset:1024
	ds_read_b128 v[182:185], v156 offset:2048
	ds_read_b128 v[186:189], v156 offset:3072
	s_add_u32 s4, s22, 0x100
	s_addc_u32 s5, s23, 0
	s_cmp_eq_u32 s48, 2
	s_cselect_b32 s25, s19, s5
	s_cselect_b32 s24, s18, s4
	s_cselect_b32 s9, s21, s47
	s_cselect_b32 s8, s20, s46
	v_lshl_add_u64 v[150:151], s[22:23], 0, v[142:143]
	s_add_i32 m0, s27, 0xc000
	ds_read_b128 v[190:193], v157
	ds_read_b128 v[194:197], v157 offset:1024
	ds_read_b128 v[198:201], v157 offset:2048
	ds_read_b128 v[202:205], v157 offset:3072
	ds_read_b128 v[210:213], v157 offset:4096
	ds_read_b128 v[214:217], v157 offset:5120
	ds_read_b128 v[218:221], v157 offset:6144
	ds_read_b128 v[222:225], v157 offset:7168
	global_load_lds_dwordx4 v[150:151], off
	v_lshl_add_u64 v[150:151], s[22:23], 0, v[144:145]
	s_add_i32 m0, s27, 0xe000
	s_nop 0
	global_load_lds_dwordx4 v[150:151], off
	s_waitcnt vmcnt(8) lgkmcnt(0)
	s_barrier
	s_setprio 1
	v_mfma_f32_16x16x32_bf16 v[124:127], v[158:161], v[190:193], v[124:127]
	v_mfma_f32_16x16x32_bf16 v[120:123], v[166:169], v[190:193], v[120:123]
	v_mfma_f32_16x16x32_bf16 v[108:111], v[158:161], v[198:201], v[108:111]
	v_mfma_f32_16x16x32_bf16 v[104:107], v[166:169], v[198:201], v[104:107]
	v_mfma_f32_16x16x32_bf16 v[92:95], v[158:161], v[210:213], v[92:95]
	v_mfma_f32_16x16x32_bf16 v[88:91], v[166:169], v[210:213], v[88:91]
	v_mfma_f32_16x16x32_bf16 v[76:79], v[158:161], v[218:221], v[76:79]
	v_mfma_f32_16x16x32_bf16 v[72:75], v[166:169], v[218:221], v[72:75]
	s_setprio 0
	s_setprio 1
	v_mfma_f32_16x16x32_bf16 v[124:127], v[162:165], v[194:197], v[124:127]
	v_mfma_f32_16x16x32_bf16 v[120:123], v[170:173], v[194:197], v[120:123]
	v_mfma_f32_16x16x32_bf16 v[108:111], v[162:165], v[202:205], v[108:111]
	v_mfma_f32_16x16x32_bf16 v[104:107], v[170:173], v[202:205], v[104:107]
	v_mfma_f32_16x16x32_bf16 v[92:95], v[162:165], v[214:217], v[92:95]
	v_mfma_f32_16x16x32_bf16 v[88:91], v[170:173], v[214:217], v[88:91]
	v_mfma_f32_16x16x32_bf16 v[76:79], v[162:165], v[222:225], v[76:79]
	v_mfma_f32_16x16x32_bf16 v[72:75], v[170:173], v[222:225], v[72:75]
	s_setprio 0
	s_setprio 1
	v_mfma_f32_16x16x32_bf16 v[116:119], v[174:177], v[190:193], v[116:119]
	v_mfma_f32_16x16x32_bf16 v[112:115], v[182:185], v[190:193], v[112:115]
	v_mfma_f32_16x16x32_bf16 v[100:103], v[174:177], v[198:201], v[100:103]
	v_mfma_f32_16x16x32_bf16 v[96:99], v[182:185], v[198:201], v[96:99]
	v_mfma_f32_16x16x32_bf16 v[84:87], v[174:177], v[210:213], v[84:87]
	v_mfma_f32_16x16x32_bf16 v[80:83], v[182:185], v[210:213], v[80:83]
	v_mfma_f32_16x16x32_bf16 v[68:71], v[174:177], v[218:221], v[68:71]
	v_mfma_f32_16x16x32_bf16 v[64:67], v[182:185], v[218:221], v[64:67]
	s_setprio 0
	s_setprio 1
	v_mfma_f32_16x16x32_bf16 v[116:119], v[178:181], v[194:197], v[116:119]
	v_mfma_f32_16x16x32_bf16 v[112:115], v[186:189], v[194:197], v[112:115]
	v_mfma_f32_16x16x32_bf16 v[100:103], v[178:181], v[202:205], v[100:103]
	v_mfma_f32_16x16x32_bf16 v[96:99], v[186:189], v[202:205], v[96:99]
	v_mfma_f32_16x16x32_bf16 v[84:87], v[178:181], v[214:217], v[84:87]
	v_mfma_f32_16x16x32_bf16 v[80:83], v[186:189], v[214:217], v[80:83]
	v_mfma_f32_16x16x32_bf16 v[68:71], v[178:181], v[222:225], v[68:71]
	v_mfma_f32_16x16x32_bf16 v[64:67], v[186:189], v[222:225], v[64:67]
	s_setprio 0
	s_barrier
	s_add_i32 s22, s39, s81
	v_lshl_add_u64 v[150:151], s[8:9], 0, v[130:131]
	s_mov_b32 m0, s22
	ds_read_b128 v[190:193], v157 offset:16384
	ds_read_b128 v[194:197], v157 offset:17408
	ds_read_b128 v[198:201], v157 offset:18432
	ds_read_b128 v[202:205], v157 offset:19456
	ds_read_b128 v[210:213], v157 offset:20480
	ds_read_b128 v[214:217], v157 offset:21504
	ds_read_b128 v[218:221], v157 offset:22528
	ds_read_b128 v[222:225], v157 offset:23552
	global_load_lds_dwordx4 v[150:151], off
	s_add_i32 m0, s22, 0x2000
	s_add_u32 s22, s8, 0x18000
	v_lshl_add_u64 v[206:207], s[8:9], 0, v[134:135]
	s_addc_u32 s23, s9, 0
	s_add_i32 s49, s40, s81
	global_load_lds_dwordx4 v[206:207], off
	v_lshl_add_u64 v[226:227], s[22:23], 0, v[130:131]
	s_mov_b32 m0, s49
	v_lshl_add_u64 v[228:229], s[24:25], 0, v[132:133]
	global_load_lds_dwordx4 v[226:227], off
	v_lshl_add_u64 v[226:227], s[22:23], 0, v[134:135]
	s_add_i32 m0, s49, 0x2000
	s_nop 0
	global_load_lds_dwordx4 v[226:227], off
	v_lshl_add_u64 v[226:227], s[24:25], 0, v[128:129]
	s_mov_b32 m0, s27
	s_nop 0
	global_load_lds_dwordx4 v[226:227], off
	s_mov_b32 m0, s28
	s_nop 0
	global_load_lds_dwordx4 v[228:229], off
	s_waitcnt vmcnt(8) lgkmcnt(0)
	s_barrier
; #define PG8_STAGE(bufoff, gbase, voff) do { _Pragma("unroll") for (int _i = 0; _i < 2; ++_i) \
;         __builtin_amdgcn_global_load_lds((const unsigned*)((const char*)(gbase) + (voff)[_i]), (LAS unsigned*)(lds + (bufoff) + ldsw + _i * 8192), 16, 0, 0); } while (0)
; #define PG8_LDA(dst, b, h) do { _Pragma("unroll") for (int m = 0; m < 4; ++m) _Pragma("unroll") for (int k = 0; k < 2; ++k) dst[m][k] = *(const LAS bf16x8*)(lds + PG8_SA(b, h) + aoff + m * 2048 + k * 1024); } while (0)
; #define PG8_LDB(dst, b, h) do { _Pragma("unroll") for (int n = 0; n < 2; ++n) _Pragma("unroll") for (int k = 0; k < 2; ++k) dst[n][k] = *(const LAS bf16x8*)(lds + PG8_SB(b, h) + boff + n * 2048 + k * 1024); } while (0)
; #define PG8_MMA(ai, bj, At, Bt) do { __builtin_amdgcn_s_setprio(1); _Pragma("unroll") for (int m = 0; m < 4; ++m) _Pragma("unroll") for (int n = 0; n < 2; ++n) _Pragma("unroll") for (int k = 0; k < 2; ++k) \
;         acc[ai][bj][m][n] = __builtin_amdgcn_mfma_f32_16x16x32_bf16(Bt[n][k], At[m][k], acc[ai][bj][m][n], 0, 0, 0); __builtin_amdgcn_s_setprio(0); } while (0)
; #define PG8_WAIT_V(n) asm volatile("s_waitcnt vmcnt(" #n ")" ::: "memory")
; #define PG8_WAIT_L(n) asm volatile("s_waitcnt lgkmcnt(" #n ")" ::: "memory")
; #define PG8_BAR __builtin_amdgcn_s_barrier()
; #define PG8_SCHED __builtin_amdgcn_sched_barrier(0)
; template <class Epi, class Sched>
; __device__ __forceinline__ void gemm_phase(LAS unsigned char* lds, const Gemm g, const Sched& S, const Epi& E, const int wave_s) {
;     ...
;             PG8_WAIT_V(8); PG8_WAIT_L(0); PG8_BAR; PG8_MMA(1, 0, At, B0); PG8_MMA(1, 1, At, B1); PG8_BAR; PG8_SCHED;
;             PG8_LDB(B0, 1, 0); PG8_LDB(B1, 1, 1); PG8_SCHED; PG8_LDA(At, 1, 0); PG8_STAGE(PG8_SA(0, 1), a2 + hstepA, voffA);
;             PG8_WAIT_V(8); PG8_WAIT_L(0); PG8_BAR; PG8_MMA(0, 0, At, B0); PG8_MMA(0, 1, At, B1); PG8_BAR; PG8_SCHED;
	s_setprio 1
	v_mfma_f32_16x16x32_bf16 v[60:63], v[158:161], v[190:193], v[60:63]
	v_mfma_f32_16x16x32_bf16 v[56:59], v[166:169], v[190:193], v[56:59]
	v_mfma_f32_16x16x32_bf16 v[44:47], v[158:161], v[198:201], v[44:47]
	v_mfma_f32_16x16x32_bf16 v[40:43], v[166:169], v[198:201], v[40:43]
	v_mfma_f32_16x16x32_bf16 v[28:31], v[158:161], v[210:213], v[28:31]
	v_mfma_f32_16x16x32_bf16 v[24:27], v[166:169], v[210:213], v[24:27]
	v_mfma_f32_16x16x32_bf16 v[12:15], v[158:161], v[218:221], v[12:15]
	v_mfma_f32_16x16x32_bf16 v[8:11], v[166:169], v[218:221], v[8:11]
	s_setprio 0
	s_setprio 1
	v_mfma_f32_16x16x32_bf16 v[60:63], v[162:165], v[194:197], v[60:63]
	v_mfma_f32_16x16x32_bf16 v[56:59], v[170:173], v[194:197], v[56:59]
	v_mfma_f32_16x16x32_bf16 v[44:47], v[162:165], v[202:205], v[44:47]
	v_mfma_f32_16x16x32_bf16 v[40:43], v[170:173], v[202:205], v[40:43]
	v_mfma_f32_16x16x32_bf16 v[28:31], v[162:165], v[214:217], v[28:31]
	v_mfma_f32_16x16x32_bf16 v[24:27], v[170:173], v[214:217], v[24:27]
	v_mfma_f32_16x16x32_bf16 v[12:15], v[162:165], v[222:225], v[12:15]
	v_mfma_f32_16x16x32_bf16 v[8:11], v[170:173], v[222:225], v[8:11]
	s_setprio 0
	s_setprio 1
	v_mfma_f32_16x16x32_bf16 v[52:55], v[174:177], v[190:193], v[52:55]
	v_mfma_f32_16x16x32_bf16 v[48:51], v[182:185], v[190:193], v[48:51]
	v_mfma_f32_16x16x32_bf16 v[36:39], v[174:177], v[198:201], v[36:39]
	v_mfma_f32_16x16x32_bf16 v[32:35], v[182:185], v[198:201], v[32:35]
	v_mfma_f32_16x16x32_bf16 v[20:23], v[174:177], v[210:213], v[20:23]
	v_mfma_f32_16x16x32_bf16 v[16:19], v[182:185], v[210:213], v[16:19]
	v_mfma_f32_16x16x32_bf16 v[4:7], v[174:177], v[218:221], v[4:7]
	v_mfma_f32_16x16x32_bf16 v[0:3], v[182:185], v[218:221], v[0:3]
	s_setprio 0
	s_setprio 1
	v_mfma_f32_16x16x32_bf16 v[52:55], v[178:181], v[194:197], v[52:55]
	v_mfma_f32_16x16x32_bf16 v[48:51], v[186:189], v[194:197], v[48:51]
	v_mfma_f32_16x16x32_bf16 v[36:39], v[178:181], v[202:205], v[36:39]
	v_mfma_f32_16x16x32_bf16 v[32:35], v[186:189], v[202:205], v[32:35]
	v_mfma_f32_16x16x32_bf16 v[20:23], v[178:181], v[214:217], v[20:23]
	v_mfma_f32_16x16x32_bf16 v[16:19], v[186:189], v[214:217], v[16:19]
	v_mfma_f32_16x16x32_bf16 v[4:7], v[178:181], v[222:225], v[4:7]
	v_mfma_f32_16x16x32_bf16 v[0:3], v[186:189], v[222:225], v[0:3]
	s_setprio 0
	s_barrier
	s_add_i32 s49, 0, 0x18000
	v_add_u32_e32 v136, s49, v153
	s_add_i32 s50, 0, 0x1c000
	ds_read_b128 v[158:161], v136
	ds_read_b128 v[162:165], v136 offset:1024
	ds_read_b128 v[166:169], v136 offset:2048
	ds_read_b128 v[170:173], v136 offset:3072
	v_add_u32_e32 v136, s50, v153
	ds_read_b128 v[174:177], v136
	ds_read_b128 v[178:181], v136 offset:1024
	ds_read_b128 v[182:185], v136 offset:2048
	ds_read_b128 v[186:189], v136 offset:3072
	s_add_u32 s22, s24, 0xf0000
	s_addc_u32 s23, s25, 0
	s_mov_b32 m0, s29
	v_lshl_add_u64 v[230:231], s[22:23], 0, v[128:129]
	ds_read_b128 v[190:193], v157 offset:32768
	ds_read_b128 v[194:197], v157 offset:33792
	ds_read_b128 v[198:201], v157 offset:34816
	ds_read_b128 v[202:205], v157 offset:35840
	ds_read_b128 v[210:213], v157 offset:36864
	ds_read_b128 v[214:217], v157 offset:37888
	ds_read_b128 v[218:221], v157 offset:38912
	ds_read_b128 v[222:225], v157 offset:39936
	global_load_lds_dwordx4 v[230:231], off
	v_lshl_add_u64 v[230:231], s[22:23], 0, v[132:133]
	s_mov_b32 m0, s30
	s_nop 0
	global_load_lds_dwordx4 v[230:231], off
	s_waitcnt vmcnt(8) lgkmcnt(0)
	s_barrier
	s_setprio 1
	v_mfma_f32_16x16x32_bf16 v[124:127], v[158:161], v[190:193], v[124:127]
	v_mfma_f32_16x16x32_bf16 v[120:123], v[166:169], v[190:193], v[120:123]
	v_mfma_f32_16x16x32_bf16 v[108:111], v[158:161], v[198:201], v[108:111]
	v_mfma_f32_16x16x32_bf16 v[104:107], v[166:169], v[198:201], v[104:107]
	v_mfma_f32_16x16x32_bf16 v[92:95], v[158:161], v[210:213], v[92:95]
	v_mfma_f32_16x16x32_bf16 v[88:91], v[166:169], v[210:213], v[88:91]
	v_mfma_f32_16x16x32_bf16 v[76:79], v[158:161], v[218:221], v[76:79]
	v_mfma_f32_16x16x32_bf16 v[72:75], v[166:169], v[218:221], v[72:75]
	s_setprio 0
	s_setprio 1
	v_mfma_f32_16x16x32_bf16 v[124:127], v[162:165], v[194:197], v[124:127]
	v_mfma_f32_16x16x32_bf16 v[120:123], v[170:173], v[194:197], v[120:123]
	v_mfma_f32_16x16x32_bf16 v[108:111], v[162:165], v[202:205], v[108:111]
	v_mfma_f32_16x16x32_bf16 v[104:107], v[170:173], v[202:205], v[104:107]
	v_mfma_f32_16x16x32_bf16 v[92:95], v[162:165], v[214:217], v[92:95]
	v_mfma_f32_16x16x32_bf16 v[88:91], v[170:173], v[214:217], v[88:91]
	v_mfma_f32_16x16x32_bf16 v[76:79], v[162:165], v[222:225], v[76:79]
	v_mfma_f32_16x16x32_bf16 v[72:75], v[170:173], v[222:225], v[72:75]
	s_setprio 0
	s_setprio 1
	v_mfma_f32_16x16x32_bf16 v[116:119], v[174:177], v[190:193], v[116:119]
	v_mfma_f32_16x16x32_bf16 v[112:115], v[182:185], v[190:193], v[112:115]
	v_mfma_f32_16x16x32_bf16 v[100:103], v[174:177], v[198:201], v[100:103]
	v_mfma_f32_16x16x32_bf16 v[96:99], v[182:185], v[198:201], v[96:99]
	v_mfma_f32_16x16x32_bf16 v[84:87], v[174:177], v[210:213], v[84:87]
	v_mfma_f32_16x16x32_bf16 v[80:83], v[182:185], v[210:213], v[80:83]
	v_mfma_f32_16x16x32_bf16 v[68:71], v[174:177], v[218:221], v[68:71]
	v_mfma_f32_16x16x32_bf16 v[64:67], v[182:185], v[218:221], v[64:67]
	s_setprio 0
	s_setprio 1
	v_mfma_f32_16x16x32_bf16 v[116:119], v[178:181], v[194:197], v[116:119]
	v_mfma_f32_16x16x32_bf16 v[112:115], v[186:189], v[194:197], v[112:115]
	v_mfma_f32_16x16x32_bf16 v[100:103], v[178:181], v[202:205], v[100:103]
	v_mfma_f32_16x16x32_bf16 v[96:99], v[186:189], v[202:205], v[96:99]
	v_mfma_f32_16x16x32_bf16 v[84:87], v[178:181], v[214:217], v[84:87]
	v_mfma_f32_16x16x32_bf16 v[80:83], v[186:189], v[214:217], v[80:83]
	v_mfma_f32_16x16x32_bf16 v[68:71], v[178:181], v[222:225], v[68:71]
	v_mfma_f32_16x16x32_bf16 v[64:67], v[186:189], v[222:225], v[64:67]
	s_setprio 0
	s_barrier
; #define PG8_STAGE(bufoff, gbase, voff) do { _Pragma("unroll") for (int _i = 0; _i < 2; ++_i) \
;         __builtin_amdgcn_global_load_lds((const unsigned*)((const char*)(gbase) + (voff)[_i]), (LAS unsigned*)(lds + (bufoff) + ldsw + _i * 8192), 16, 0, 0); } while (0)
; #define PG8_LDA(dst, b, h) do { _Pragma("unroll") for (int m = 0; m < 4; ++m) _Pragma("unroll") for (int k = 0; k < 2; ++k) dst[m][k] = *(const LAS bf16x8*)(lds + PG8_SA(b, h) + aoff + m * 2048 + k * 1024); } while (0)
; #define PG8_MMA(ai, bj, At, Bt) do { __builtin_amdgcn_s_setprio(1); _Pragma("unroll") for (int m = 0; m < 4; ++m) _Pragma("unroll") for (int n = 0; n < 2; ++n) _Pragma("unroll") for (int k = 0; k < 2; ++k) \
;         acc[ai][bj][m][n] = __builtin_amdgcn_mfma_f32_16x16x32_bf16(Bt[n][k], At[m][k], acc[ai][bj][m][n], 0, 0, 0); __builtin_amdgcn_s_setprio(0); } while (0)
; #define PG8_WAIT_V(n) asm volatile("s_waitcnt vmcnt(" #n ")" ::: "memory")
; #define PG8_WAIT_L(n) asm volatile("s_waitcnt lgkmcnt(" #n ")" ::: "memory")
; #define PG8_BAR __builtin_amdgcn_s_barrier()
; #define PG8_SCHED __builtin_amdgcn_sched_barrier(0)
; template <class Epi, class Sched>
; __device__ __forceinline__ void gemm_phase(LAS unsigned char* lds, const Gemm g, const Sched& S, const Epi& E, const int wave_s) {
;     ...
;             PG8_LDA(At, 1, 1); PG8_STAGE(PG8_SB(1, 0), b3, voffB); PG8_STAGE(PG8_SB(1, 1), b3 + hstepB, voffB); PG8_STAGE(PG8_SA(1, 0), a3, voffA);
;             PG8_WAIT_V(8); PG8_WAIT_L(0); PG8_BAR; PG8_MMA(1, 0, At, B0); PG8_MMA(1, 1, At, B1); PG8_BAR; PG8_SCHED;
;         }
	s_add_i32 s22, s49, s81
	v_lshl_add_u64 v[150:151], v[150:151], 0, s[14:15]
	s_mov_b32 m0, s22
	ds_read_b128 v[190:193], v157 offset:49152
	ds_read_b128 v[194:197], v157 offset:50176
	ds_read_b128 v[198:201], v157 offset:51200
	ds_read_b128 v[202:205], v157 offset:52224
	ds_read_b128 v[210:213], v157 offset:53248
	ds_read_b128 v[214:217], v157 offset:54272
	ds_read_b128 v[218:221], v157 offset:55296
	ds_read_b128 v[222:225], v157 offset:56320
	global_load_lds_dwordx4 v[150:151], off
	s_add_i32 m0, s22, 0x2000
	s_add_u32 s8, s8, 0x18080
	v_lshl_add_u64 v[150:151], v[206:207], 0, s[14:15]
	s_addc_u32 s9, s9, 0
	s_add_i32 s22, s50, s81
	global_load_lds_dwordx4 v[150:151], off
	v_lshl_add_u64 v[150:151], s[8:9], 0, v[130:131]
	s_mov_b32 m0, s22
	s_nop 0
	global_load_lds_dwordx4 v[150:151], off
	v_lshl_add_u64 v[150:151], s[8:9], 0, v[134:135]
	s_add_i32 m0, s22, 0x2000
	s_nop 0
	global_load_lds_dwordx4 v[150:151], off
	v_lshl_add_u64 v[150:151], v[226:227], 0, s[14:15]
	s_mov_b32 m0, s33
	s_nop 0
	global_load_lds_dwordx4 v[150:151], off
	v_lshl_add_u64 v[150:151], v[228:229], 0, s[14:15]
	s_mov_b32 m0, s34
	s_nop 0
	global_load_lds_dwordx4 v[150:151], off
	s_waitcnt vmcnt(8) lgkmcnt(0)
	s_barrier
	s_setprio 1
	v_mfma_f32_16x16x32_bf16 v[60:63], v[158:161], v[190:193], v[60:63]
	v_mfma_f32_16x16x32_bf16 v[56:59], v[166:169], v[190:193], v[56:59]
	v_mfma_f32_16x16x32_bf16 v[44:47], v[158:161], v[198:201], v[44:47]
	v_mfma_f32_16x16x32_bf16 v[40:43], v[166:169], v[198:201], v[40:43]
	v_mfma_f32_16x16x32_bf16 v[28:31], v[158:161], v[210:213], v[28:31]
	v_mfma_f32_16x16x32_bf16 v[24:27], v[166:169], v[210:213], v[24:27]
	v_mfma_f32_16x16x32_bf16 v[12:15], v[158:161], v[218:221], v[12:15]
	v_mfma_f32_16x16x32_bf16 v[8:11], v[166:169], v[218:221], v[8:11]
	s_setprio 0
	s_setprio 1
	v_mfma_f32_16x16x32_bf16 v[60:63], v[162:165], v[194:197], v[60:63]
	v_mfma_f32_16x16x32_bf16 v[56:59], v[170:173], v[194:197], v[56:59]
	v_mfma_f32_16x16x32_bf16 v[44:47], v[162:165], v[202:205], v[44:47]
	v_mfma_f32_16x16x32_bf16 v[40:43], v[170:173], v[202:205], v[40:43]
	v_mfma_f32_16x16x32_bf16 v[28:31], v[162:165], v[214:217], v[28:31]
	v_mfma_f32_16x16x32_bf16 v[24:27], v[170:173], v[214:217], v[24:27]
	v_mfma_f32_16x16x32_bf16 v[12:15], v[162:165], v[222:225], v[12:15]
	v_mfma_f32_16x16x32_bf16 v[8:11], v[170:173], v[222:225], v[8:11]
	s_setprio 0
	s_setprio 1
	v_mfma_f32_16x16x32_bf16 v[52:55], v[174:177], v[190:193], v[52:55]
	v_mfma_f32_16x16x32_bf16 v[48:51], v[182:185], v[190:193], v[48:51]
	v_mfma_f32_16x16x32_bf16 v[36:39], v[174:177], v[198:201], v[36:39]
	v_mfma_f32_16x16x32_bf16 v[32:35], v[182:185], v[198:201], v[32:35]
	v_mfma_f32_16x16x32_bf16 v[20:23], v[174:177], v[210:213], v[20:23]
	v_mfma_f32_16x16x32_bf16 v[16:19], v[182:185], v[210:213], v[16:19]
	v_mfma_f32_16x16x32_bf16 v[4:7], v[174:177], v[218:221], v[4:7]
	v_mfma_f32_16x16x32_bf16 v[0:3], v[182:185], v[218:221], v[0:3]
	s_setprio 0
	s_setprio 1
	v_mfma_f32_16x16x32_bf16 v[52:55], v[178:181], v[194:197], v[52:55]
	v_mfma_f32_16x16x32_bf16 v[48:51], v[186:189], v[194:197], v[48:51]
	v_mfma_f32_16x16x32_bf16 v[36:39], v[178:181], v[202:205], v[36:39]
	v_mfma_f32_16x16x32_bf16 v[32:35], v[186:189], v[202:205], v[32:35]
	v_mfma_f32_16x16x32_bf16 v[20:23], v[178:181], v[214:217], v[20:23]
	v_mfma_f32_16x16x32_bf16 v[16:19], v[186:189], v[214:217], v[16:19]
	v_mfma_f32_16x16x32_bf16 v[4:7], v[178:181], v[222:225], v[4:7]
	v_mfma_f32_16x16x32_bf16 v[0:3], v[186:189], v[222:225], v[0:3]
	s_setprio 0
	s_barrier
	s_add_i32 s48, s48, 2
	s_add_u32 s46, s46, 0x100
	s_addc_u32 s47, s47, 0
	s_cmp_gt_u32 s48, 3
	s_mov_b64 s[22:23], s[4:5]
	s_cbranch_scc0 .LBB0_375
	s_and_b64 vcc, exec, s[16:17]
	s_cbranch_vccz .LBB0_378
	s_barrier

; #define PG8_STAGE(bufoff, gbase, voff) do { _Pragma("unroll") for (int _i = 0; _i < 2; ++_i) \
;         __builtin_amdgcn_global_load_lds((const unsigned*)((const char*)(gbase) + (voff)[_i]), (LAS unsigned*)(lds + (bufoff) + ldsw + _i * 8192), 16, 0, 0); } while (0)
; #define PG8_LDA(dst, b, h) do { _Pragma("unroll") for (int m = 0; m < 4; ++m) _Pragma("unroll") for (int k = 0; k < 2; ++k) dst[m][k] = *(const LAS bf16x8*)(lds + PG8_SA(b, h) + aoff + m * 2048 + k * 1024); } while (0)
; #define PG8_LDB(dst, b, h) do { _Pragma("unroll") for (int n = 0; n < 2; ++n) _Pragma("unroll") for (int k = 0; k < 2; ++k) dst[n][k] = *(const LAS bf16x8*)(lds + PG8_SB(b, h) + boff + n * 2048 + k * 1024); } while (0)
; #define PG8_MMA(ai, bj, At, Bt) do { __builtin_amdgcn_s_setprio(1); _Pragma("unroll") for (int m = 0; m < 4; ++m) _Pragma("unroll") for (int n = 0; n < 2; ++n) _Pragma("unroll") for (int k = 0; k < 2; ++k) \
;         acc[ai][bj][m][n] = __builtin_amdgcn_mfma_f32_16x16x32_bf16(Bt[n][k], At[m][k], acc[ai][bj][m][n], 0, 0, 0); __builtin_amdgcn_s_setprio(0); } while (0)
; #define PG8_BAR __builtin_amdgcn_s_barrier()
; template <class Epi, class Sched>
; __device__ __forceinline__ void gemm_phase(LAS unsigned char* lds, const Gemm g, const Sched& S, const Epi& E, const int wave_s) {
;     ...
;         const char* nA = has_next ? (const char*)g.A + (size_t)nxt.pm * tstepA + (size_t)nxt.acol * 2 : cA; const char* nB = has_next ? (const char*)g.Bt + (size_t)nxt.pn * tstepB : cB;
; #pragma unroll 1
;         for (int t = 0; t < nt; t += 2) {
;             const bool last = (t == nt - 2);
;             const char* a1 = cA + (size_t)(t + 1) * kstep;
;             const char* a2 = last ? nA : cA + (size_t)(t + 2) * kstep; const char* b2 = last ? nB : cB + (size_t)(t + 2) * kstep;
;             const char* a3 = a2 + kstep; const char* b3 = b2 + kstep;
;             PG8_LDB(B0, 0, 0); PG8_LDB(B1, 0, 1); PG8_SCHED; PG8_LDA(At, 0, 0); PG8_STAGE(PG8_SA(1, 1), a1 + hstepA, voffA);
;             PG8_WAIT_V(8); PG8_WAIT_L(0); PG8_BAR; PG8_MMA(0, 0, At, B0); PG8_MMA(0, 1, At, B1); PG8_BAR; PG8_SCHED;
;             PG8_LDA(At, 0, 1); PG8_STAGE(PG8_SB(0, 0), b2, voffB); PG8_STAGE(PG8_SB(0, 1), b2 + hstepB, voffB); PG8_STAGE(PG8_SA(0, 0), a2, voffA);
;             PG8_WAIT_V(8); PG8_WAIT_L(0); PG8_BAR; PG8_MMA(1, 0, At, B0); PG8_MMA(1, 1, At, B1); PG8_BAR; PG8_SCHED;
.LBB0_417:
	s_add_u32 s39, s36, s38
	s_addc_u32 s44, s37, 0
	s_add_u32 s42, s39, 0x100
	s_addc_u32 s43, s44, 0
	s_and_b64 s[40:41], s[4:5], exec
	s_cselect_b32 s41, s29, s43
	s_cselect_b32 s40, s28, s42
	s_add_u32 s38, s34, s38
	s_addc_u32 s42, s35, 0
	s_add_u32 s38, s38, 0x100
	s_addc_u32 s42, s42, 0
	s_and_b64 s[4:5], s[4:5], exec
	s_cselect_b32 s43, s27, s42
	s_cselect_b32 s42, s68, s38
	s_add_u32 s46, s39, 0xf0080
	ds_read_b128 v[148:151], v145
	ds_read_b128 v[152:155], v145 offset:1024
	ds_read_b128 v[156:159], v145 offset:2048
	ds_read_b128 v[160:163], v145 offset:3072
	ds_read_b128 v[164:167], v146
	ds_read_b128 v[168:171], v146 offset:1024
	ds_read_b128 v[172:175], v146 offset:2048
	ds_read_b128 v[176:179], v146 offset:3072
	s_addc_u32 s47, s44, 0
	s_add_i32 s76, s59, s81
	s_add_i32 m0, s49, 0xc000
	s_add_i32 s79, s49, 0xe000
	s_add_i32 s73, s76, 0x2000
	s_add_u32 s44, s42, 0x10000
	s_addc_u32 s45, s43, 0
	s_add_i32 s75, s60, s81
	s_add_i32 s74, s75, 0x2000
	s_add_i32 s72, 0, 0x18000
	s_add_i32 s71, 0, 0x1c000
	s_add_u32 s38, s40, 0xf0000
	s_addc_u32 s39, s41, 0
	s_add_i32 s70, s72, s81
	s_add_i32 s69, s70, 0x2000
	s_add_u32 s4, s42, 0x10080
	s_addc_u32 s5, s43, 0
	s_add_i32 s78, s71, s81
	s_add_i32 s77, s78, 0x2000
	v_lshl_add_u64 v[140:141], s[46:47], 0, v[128:129]
	ds_read_b128 v[180:183], v147
	ds_read_b128 v[184:187], v147 offset:1024
	ds_read_b128 v[188:191], v147 offset:2048
	ds_read_b128 v[192:195], v147 offset:3072
	ds_read_b128 v[196:199], v147 offset:4096
	ds_read_b128 v[200:203], v147 offset:5120
	ds_read_b128 v[204:207], v147 offset:6144
	ds_read_b128 v[210:213], v147 offset:7168
	global_load_lds_dwordx4 v[140:141], off
	v_lshl_add_u64 v[140:141], s[46:47], 0, v[132:133]
	s_mov_b32 m0, s79
	s_nop 0
	global_load_lds_dwordx4 v[140:141], off
	s_waitcnt vmcnt(8) lgkmcnt(0)
	s_barrier
	s_setprio 1
	v_mfma_f32_16x16x32_bf16 v[124:127], v[148:151], v[180:183], v[124:127]
	v_mfma_f32_16x16x32_bf16 v[120:123], v[156:159], v[180:183], v[120:123]
	v_mfma_f32_16x16x32_bf16 v[116:119], v[148:151], v[188:191], v[116:119]
	v_mfma_f32_16x16x32_bf16 v[108:111], v[156:159], v[188:191], v[108:111]
	v_mfma_f32_16x16x32_bf16 v[100:103], v[148:151], v[196:199], v[100:103]
	v_mfma_f32_16x16x32_bf16 v[92:95], v[156:159], v[196:199], v[92:95]
	v_mfma_f32_16x16x32_bf16 v[84:87], v[148:151], v[204:207], v[84:87]
	v_mfma_f32_16x16x32_bf16 v[76:79], v[156:159], v[204:207], v[76:79]
	s_setprio 0
	s_setprio 1
	v_mfma_f32_16x16x32_bf16 v[124:127], v[152:155], v[184:187], v[124:127]
	v_mfma_f32_16x16x32_bf16 v[120:123], v[160:163], v[184:187], v[120:123]
	v_mfma_f32_16x16x32_bf16 v[116:119], v[152:155], v[192:195], v[116:119]
	v_mfma_f32_16x16x32_bf16 v[108:111], v[160:163], v[192:195], v[108:111]
	v_mfma_f32_16x16x32_bf16 v[100:103], v[152:155], v[200:203], v[100:103]
	v_mfma_f32_16x16x32_bf16 v[92:95], v[160:163], v[200:203], v[92:95]
	v_mfma_f32_16x16x32_bf16 v[84:87], v[152:155], v[210:213], v[84:87]
	v_mfma_f32_16x16x32_bf16 v[76:79], v[160:163], v[210:213], v[76:79]
	s_setprio 0
	s_setprio 1
	v_mfma_f32_16x16x32_bf16 v[112:115], v[164:167], v[180:183], v[112:115]
	v_mfma_f32_16x16x32_bf16 v[104:107], v[172:175], v[180:183], v[104:107]
	v_mfma_f32_16x16x32_bf16 v[96:99], v[164:167], v[188:191], v[96:99]
	v_mfma_f32_16x16x32_bf16 v[88:91], v[172:175], v[188:191], v[88:91]
	v_mfma_f32_16x16x32_bf16 v[80:83], v[164:167], v[196:199], v[80:83]
	v_mfma_f32_16x16x32_bf16 v[72:75], v[172:175], v[196:199], v[72:75]
	v_mfma_f32_16x16x32_bf16 v[68:71], v[164:167], v[204:207], v[68:71]
	v_mfma_f32_16x16x32_bf16 v[64:67], v[172:175], v[204:207], v[64:67]
	s_setprio 0
	s_setprio 1
	v_mfma_f32_16x16x32_bf16 v[112:115], v[168:171], v[184:187], v[112:115]
	v_mfma_f32_16x16x32_bf16 v[104:107], v[176:179], v[184:187], v[104:107]
	v_mfma_f32_16x16x32_bf16 v[96:99], v[168:171], v[192:195], v[96:99]
	v_mfma_f32_16x16x32_bf16 v[88:91], v[176:179], v[192:195], v[88:91]
	v_mfma_f32_16x16x32_bf16 v[80:83], v[168:171], v[200:203], v[80:83]
	v_mfma_f32_16x16x32_bf16 v[72:75], v[176:179], v[200:203], v[72:75]
	v_mfma_f32_16x16x32_bf16 v[68:71], v[168:171], v[210:213], v[68:71]
	v_mfma_f32_16x16x32_bf16 v[64:67], v[176:179], v[210:213], v[64:67]
	s_setprio 0
	s_barrier
	s_mov_b32 m0, s76
	v_lshl_add_u64 v[140:141], s[42:43], 0, v[130:131]
	ds_read_b128 v[180:183], v147 offset:16384
	ds_read_b128 v[184:187], v147 offset:17408
	ds_read_b128 v[188:191], v147 offset:18432
	ds_read_b128 v[192:195], v147 offset:19456
	ds_read_b128 v[196:199], v147 offset:20480
	ds_read_b128 v[200:203], v147 offset:21504
	ds_read_b128 v[204:207], v147 offset:22528
	ds_read_b128 v[210:213], v147 offset:23552
	global_load_lds_dwordx4 v[140:141], off
	v_lshl_add_u64 v[214:215], s[42:43], 0, v[134:135]
	s_mov_b32 m0, s73
	v_lshl_add_u64 v[216:217], s[44:45], 0, v[130:131]
	global_load_lds_dwordx4 v[214:215], off
	s_mov_b32 m0, s75
	v_lshl_add_u64 v[218:219], s[40:41], 0, v[132:133]
	global_load_lds_dwordx4 v[216:217], off
	v_lshl_add_u64 v[216:217], s[44:45], 0, v[134:135]
	s_mov_b32 m0, s74
	s_nop 0
	global_load_lds_dwordx4 v[216:217], off
	v_lshl_add_u64 v[216:217], s[40:41], 0, v[128:129]
	s_mov_b32 m0, s49
	s_nop 0
	global_load_lds_dwordx4 v[216:217], off
	s_mov_b32 m0, s50
	s_nop 0
	global_load_lds_dwordx4 v[218:219], off
	s_waitcnt vmcnt(8) lgkmcnt(0)
	s_barrier
; #define PG8_STAGE(bufoff, gbase, voff) do { _Pragma("unroll") for (int _i = 0; _i < 2; ++_i) \
;         __builtin_amdgcn_global_load_lds((const unsigned*)((const char*)(gbase) + (voff)[_i]), (LAS unsigned*)(lds + (bufoff) + ldsw + _i * 8192), 16, 0, 0); } while (0)
; #define PG8_LDA(dst, b, h) do { _Pragma("unroll") for (int m = 0; m < 4; ++m) _Pragma("unroll") for (int k = 0; k < 2; ++k) dst[m][k] = *(const LAS bf16x8*)(lds + PG8_SA(b, h) + aoff + m * 2048 + k * 1024); } while (0)
; #define PG8_LDB(dst, b, h) do { _Pragma("unroll") for (int n = 0; n < 2; ++n) _Pragma("unroll") for (int k = 0; k < 2; ++k) dst[n][k] = *(const LAS bf16x8*)(lds + PG8_SB(b, h) + boff + n * 2048 + k * 1024); } while (0)
; #define PG8_MMA(ai, bj, At, Bt) do { __builtin_amdgcn_s_setprio(1); _Pragma("unroll") for (int m = 0; m < 4; ++m) _Pragma("unroll") for (int n = 0; n < 2; ++n) _Pragma("unroll") for (int k = 0; k < 2; ++k) \
;         acc[ai][bj][m][n] = __builtin_amdgcn_mfma_f32_16x16x32_bf16(Bt[n][k], At[m][k], acc[ai][bj][m][n], 0, 0, 0); __builtin_amdgcn_s_setprio(0); } while (0)
; #define PG8_WAIT_V(n) asm volatile("s_waitcnt vmcnt(" #n ")" ::: "memory")
; #define PG8_WAIT_L(n) asm volatile("s_waitcnt lgkmcnt(" #n ")" ::: "memory")
; #define PG8_BAR __builtin_amdgcn_s_barrier()
; #define PG8_SCHED __builtin_amdgcn_sched_barrier(0)
; template <class Epi, class Sched>
; __device__ __forceinline__ void gemm_phase(LAS unsigned char* lds, const Gemm g, const Sched& S, const Epi& E, const int wave_s) {
;     ...
;             PG8_WAIT_V(8); PG8_WAIT_L(0); PG8_BAR; PG8_MMA(1, 0, At, B0); PG8_MMA(1, 1, At, B1); PG8_BAR; PG8_SCHED;
;             PG8_LDB(B0, 1, 0); PG8_LDB(B1, 1, 1); PG8_SCHED; PG8_LDA(At, 1, 0); PG8_STAGE(PG8_SA(0, 1), a2 + hstepA, voffA);
;             PG8_WAIT_V(8); PG8_WAIT_L(0); PG8_BAR; PG8_MMA(0, 0, At, B0); PG8_MMA(0, 1, At, B1); PG8_BAR; PG8_SCHED;
	s_setprio 1
	v_mfma_f32_16x16x32_bf16 v[60:63], v[148:151], v[180:183], v[60:63]
	v_mfma_f32_16x16x32_bf16 v[56:59], v[156:159], v[180:183], v[56:59]
	v_mfma_f32_16x16x32_bf16 v[52:55], v[148:151], v[188:191], v[52:55]
	v_mfma_f32_16x16x32_bf16 v[44:47], v[156:159], v[188:191], v[44:47]
	v_mfma_f32_16x16x32_bf16 v[36:39], v[148:151], v[196:199], v[36:39]
	v_mfma_f32_16x16x32_bf16 v[28:31], v[156:159], v[196:199], v[28:31]
	v_mfma_f32_16x16x32_bf16 v[20:23], v[148:151], v[204:207], v[20:23]
	v_mfma_f32_16x16x32_bf16 v[12:15], v[156:159], v[204:207], v[12:15]
	s_setprio 0
	s_setprio 1
	v_mfma_f32_16x16x32_bf16 v[60:63], v[152:155], v[184:187], v[60:63]
	v_mfma_f32_16x16x32_bf16 v[56:59], v[160:163], v[184:187], v[56:59]
	v_mfma_f32_16x16x32_bf16 v[52:55], v[152:155], v[192:195], v[52:55]
	v_mfma_f32_16x16x32_bf16 v[44:47], v[160:163], v[192:195], v[44:47]
	v_mfma_f32_16x16x32_bf16 v[36:39], v[152:155], v[200:203], v[36:39]
	v_mfma_f32_16x16x32_bf16 v[28:31], v[160:163], v[200:203], v[28:31]
	v_mfma_f32_16x16x32_bf16 v[20:23], v[152:155], v[210:213], v[20:23]
	v_mfma_f32_16x16x32_bf16 v[12:15], v[160:163], v[210:213], v[12:15]
	s_setprio 0
	s_setprio 1
	v_mfma_f32_16x16x32_bf16 v[48:51], v[164:167], v[180:183], v[48:51]
	v_mfma_f32_16x16x32_bf16 v[40:43], v[172:175], v[180:183], v[40:43]
	v_mfma_f32_16x16x32_bf16 v[32:35], v[164:167], v[188:191], v[32:35]
	v_mfma_f32_16x16x32_bf16 v[24:27], v[172:175], v[188:191], v[24:27]
	v_mfma_f32_16x16x32_bf16 v[16:19], v[164:167], v[196:199], v[16:19]
	v_mfma_f32_16x16x32_bf16 v[8:11], v[172:175], v[196:199], v[8:11]
	v_mfma_f32_16x16x32_bf16 v[4:7], v[164:167], v[204:207], v[4:7]
	v_mfma_f32_16x16x32_bf16 v[0:3], v[172:175], v[204:207], v[0:3]
	s_setprio 0
	s_setprio 1
	v_mfma_f32_16x16x32_bf16 v[48:51], v[168:171], v[184:187], v[48:51]
	v_mfma_f32_16x16x32_bf16 v[40:43], v[176:179], v[184:187], v[40:43]
	v_mfma_f32_16x16x32_bf16 v[32:35], v[168:171], v[192:195], v[32:35]
	v_mfma_f32_16x16x32_bf16 v[24:27], v[176:179], v[192:195], v[24:27]
	v_mfma_f32_16x16x32_bf16 v[16:19], v[168:171], v[200:203], v[16:19]
	v_mfma_f32_16x16x32_bf16 v[8:11], v[176:179], v[200:203], v[8:11]
	v_mfma_f32_16x16x32_bf16 v[4:7], v[168:171], v[210:213], v[4:7]
	v_mfma_f32_16x16x32_bf16 v[0:3], v[176:179], v[210:213], v[0:3]
	s_setprio 0
	s_barrier
	v_add_u32_e32 v160, s72, v143
	v_add_u32_e32 v176, s71, v143
	ds_read_b128 v[148:151], v160
	ds_read_b128 v[152:155], v160 offset:1024
	ds_read_b128 v[156:159], v160 offset:2048
	ds_read_b128 v[160:163], v160 offset:3072
	ds_read_b128 v[164:167], v176
	ds_read_b128 v[168:171], v176 offset:1024
	ds_read_b128 v[172:175], v176 offset:2048
	ds_read_b128 v[176:179], v176 offset:3072
	s_mov_b32 m0, s51
	v_lshl_add_u64 v[220:221], s[38:39], 0, v[128:129]
	ds_read_b128 v[180:183], v147 offset:32768
	ds_read_b128 v[184:187], v147 offset:33792
	ds_read_b128 v[188:191], v147 offset:34816
	ds_read_b128 v[192:195], v147 offset:35840
	ds_read_b128 v[196:199], v147 offset:36864
	ds_read_b128 v[200:203], v147 offset:37888
	ds_read_b128 v[204:207], v147 offset:38912
	ds_read_b128 v[210:213], v147 offset:39936
	global_load_lds_dwordx4 v[220:221], off
	v_lshl_add_u64 v[220:221], s[38:39], 0, v[132:133]
	s_mov_b32 m0, s52
	s_nop 0
	global_load_lds_dwordx4 v[220:221], off
	s_waitcnt vmcnt(8) lgkmcnt(0)
	s_barrier
	s_setprio 1
	v_mfma_f32_16x16x32_bf16 v[124:127], v[148:151], v[180:183], v[124:127]
	v_mfma_f32_16x16x32_bf16 v[120:123], v[156:159], v[180:183], v[120:123]
	v_mfma_f32_16x16x32_bf16 v[116:119], v[148:151], v[188:191], v[116:119]
	v_mfma_f32_16x16x32_bf16 v[108:111], v[156:159], v[188:191], v[108:111]
	v_mfma_f32_16x16x32_bf16 v[100:103], v[148:151], v[196:199], v[100:103]
	v_mfma_f32_16x16x32_bf16 v[92:95], v[156:159], v[196:199], v[92:95]
	v_mfma_f32_16x16x32_bf16 v[84:87], v[148:151], v[204:207], v[84:87]
	v_mfma_f32_16x16x32_bf16 v[76:79], v[156:159], v[204:207], v[76:79]
	s_setprio 0
	s_setprio 1
	v_mfma_f32_16x16x32_bf16 v[124:127], v[152:155], v[184:187], v[124:127]
	v_mfma_f32_16x16x32_bf16 v[120:123], v[160:163], v[184:187], v[120:123]
	v_mfma_f32_16x16x32_bf16 v[116:119], v[152:155], v[192:195], v[116:119]
	v_mfma_f32_16x16x32_bf16 v[108:111], v[160:163], v[192:195], v[108:111]
	v_mfma_f32_16x16x32_bf16 v[100:103], v[152:155], v[200:203], v[100:103]
	v_mfma_f32_16x16x32_bf16 v[92:95], v[160:163], v[200:203], v[92:95]
	v_mfma_f32_16x16x32_bf16 v[84:87], v[152:155], v[210:213], v[84:87]
	v_mfma_f32_16x16x32_bf16 v[76:79], v[160:163], v[210:213], v[76:79]
	s_setprio 0
	s_setprio 1
	v_mfma_f32_16x16x32_bf16 v[112:115], v[164:167], v[180:183], v[112:115]
	v_mfma_f32_16x16x32_bf16 v[104:107], v[172:175], v[180:183], v[104:107]
	v_mfma_f32_16x16x32_bf16 v[96:99], v[164:167], v[188:191], v[96:99]
	v_mfma_f32_16x16x32_bf16 v[88:91], v[172:175], v[188:191], v[88:91]
	v_mfma_f32_16x16x32_bf16 v[80:83], v[164:167], v[196:199], v[80:83]
	v_mfma_f32_16x16x32_bf16 v[72:75], v[172:175], v[196:199], v[72:75]
	v_mfma_f32_16x16x32_bf16 v[68:71], v[164:167], v[204:207], v[68:71]
	v_mfma_f32_16x16x32_bf16 v[64:67], v[172:175], v[204:207], v[64:67]
	s_setprio 0
	s_setprio 1
	v_mfma_f32_16x16x32_bf16 v[112:115], v[168:171], v[184:187], v[112:115]
	v_mfma_f32_16x16x32_bf16 v[104:107], v[176:179], v[184:187], v[104:107]
	v_mfma_f32_16x16x32_bf16 v[96:99], v[168:171], v[192:195], v[96:99]
	v_mfma_f32_16x16x32_bf16 v[88:91], v[176:179], v[192:195], v[88:91]
	v_mfma_f32_16x16x32_bf16 v[80:83], v[168:171], v[200:203], v[80:83]
	v_mfma_f32_16x16x32_bf16 v[72:75], v[176:179], v[200:203], v[72:75]
	v_mfma_f32_16x16x32_bf16 v[68:71], v[168:171], v[210:213], v[68:71]
	v_mfma_f32_16x16x32_bf16 v[64:67], v[176:179], v[210:213], v[64:67]
	s_setprio 0
	s_barrier
; #define PG8_STAGE(bufoff, gbase, voff) do { _Pragma("unroll") for (int _i = 0; _i < 2; ++_i) \
;         __builtin_amdgcn_global_load_lds((const unsigned*)((const char*)(gbase) + (voff)[_i]), (LAS unsigned*)(lds + (bufoff) + ldsw + _i * 8192), 16, 0, 0); } while (0)
; #define PG8_LDA(dst, b, h) do { _Pragma("unroll") for (int m = 0; m < 4; ++m) _Pragma("unroll") for (int k = 0; k < 2; ++k) dst[m][k] = *(const LAS bf16x8*)(lds + PG8_SA(b, h) + aoff + m * 2048 + k * 1024); } while (0)
; #define PG8_MMA(ai, bj, At, Bt) do { __builtin_amdgcn_s_setprio(1); _Pragma("unroll") for (int m = 0; m < 4; ++m) _Pragma("unroll") for (int n = 0; n < 2; ++n) _Pragma("unroll") for (int k = 0; k < 2; ++k) \
;         acc[ai][bj][m][n] = __builtin_amdgcn_mfma_f32_16x16x32_bf16(Bt[n][k], At[m][k], acc[ai][bj][m][n], 0, 0, 0); __builtin_amdgcn_s_setprio(0); } while (0)
; #define PG8_WAIT_V(n) asm volatile("s_waitcnt vmcnt(" #n ")" ::: "memory")
; #define PG8_WAIT_L(n) asm volatile("s_waitcnt lgkmcnt(" #n ")" ::: "memory")
; #define PG8_BAR __builtin_amdgcn_s_barrier()
; #define PG8_SCHED __builtin_amdgcn_sched_barrier(0)
; template <class Epi, class Sched>
; __device__ __forceinline__ void gemm_phase(LAS unsigned char* lds, const Gemm g, const Sched& S, const Epi& E, const int wave_s) {
;     ...
;             PG8_LDA(At, 1, 1); PG8_STAGE(PG8_SB(1, 0), b3, voffB); PG8_STAGE(PG8_SB(1, 1), b3 + hstepB, voffB); PG8_STAGE(PG8_SA(1, 0), a3, voffA);
;             PG8_WAIT_V(8); PG8_WAIT_L(0); PG8_BAR; PG8_MMA(1, 0, At, B0); PG8_MMA(1, 1, At, B1); PG8_BAR; PG8_SCHED;
;         }
	s_mov_b32 m0, s70
	v_lshl_add_u64 v[140:141], v[140:141], 0, s[14:15]
	ds_read_b128 v[180:183], v147 offset:49152
	ds_read_b128 v[184:187], v147 offset:50176
	ds_read_b128 v[188:191], v147 offset:51200
	ds_read_b128 v[192:195], v147 offset:52224
	ds_read_b128 v[196:199], v147 offset:53248
	ds_read_b128 v[200:203], v147 offset:54272
	ds_read_b128 v[204:207], v147 offset:55296
	ds_read_b128 v[210:213], v147 offset:56320
	global_load_lds_dwordx4 v[140:141], off
	v_lshl_add_u64 v[140:141], v[214:215], 0, s[14:15]
	s_mov_b32 m0, s69
	s_nop 0
	global_load_lds_dwordx4 v[140:141], off
	v_lshl_add_u64 v[140:141], s[4:5], 0, v[130:131]
	s_mov_b32 m0, s78
	s_nop 0
	global_load_lds_dwordx4 v[140:141], off
	v_lshl_add_u64 v[140:141], s[4:5], 0, v[134:135]
	s_mov_b32 m0, s77
	s_nop 0
	global_load_lds_dwordx4 v[140:141], off
	v_lshl_add_u64 v[140:141], v[216:217], 0, s[14:15]
	s_mov_b32 m0, s54
	s_nop 0
	global_load_lds_dwordx4 v[140:141], off
	v_lshl_add_u64 v[140:141], v[218:219], 0, s[14:15]
	s_mov_b32 m0, s55
	s_nop 0
	global_load_lds_dwordx4 v[140:141], off
	s_waitcnt vmcnt(8) lgkmcnt(0)
	s_barrier
	s_setprio 1
	v_mfma_f32_16x16x32_bf16 v[60:63], v[148:151], v[180:183], v[60:63]
	v_mfma_f32_16x16x32_bf16 v[56:59], v[156:159], v[180:183], v[56:59]
	v_mfma_f32_16x16x32_bf16 v[52:55], v[148:151], v[188:191], v[52:55]
	v_mfma_f32_16x16x32_bf16 v[44:47], v[156:159], v[188:191], v[44:47]
	v_mfma_f32_16x16x32_bf16 v[36:39], v[148:151], v[196:199], v[36:39]
	v_mfma_f32_16x16x32_bf16 v[28:31], v[156:159], v[196:199], v[28:31]
	v_mfma_f32_16x16x32_bf16 v[20:23], v[148:151], v[204:207], v[20:23]
	v_mfma_f32_16x16x32_bf16 v[12:15], v[156:159], v[204:207], v[12:15]
	s_setprio 0
	s_setprio 1
	v_mfma_f32_16x16x32_bf16 v[60:63], v[152:155], v[184:187], v[60:63]
	v_mfma_f32_16x16x32_bf16 v[56:59], v[160:163], v[184:187], v[56:59]
	v_mfma_f32_16x16x32_bf16 v[52:55], v[152:155], v[192:195], v[52:55]
	v_mfma_f32_16x16x32_bf16 v[44:47], v[160:163], v[192:195], v[44:47]
	v_mfma_f32_16x16x32_bf16 v[36:39], v[152:155], v[200:203], v[36:39]
	v_mfma_f32_16x16x32_bf16 v[28:31], v[160:163], v[200:203], v[28:31]
	v_mfma_f32_16x16x32_bf16 v[20:23], v[152:155], v[210:213], v[20:23]
	v_mfma_f32_16x16x32_bf16 v[12:15], v[160:163], v[210:213], v[12:15]
	s_setprio 0
	s_setprio 1
	v_mfma_f32_16x16x32_bf16 v[48:51], v[164:167], v[180:183], v[48:51]
	v_mfma_f32_16x16x32_bf16 v[40:43], v[172:175], v[180:183], v[40:43]
	v_mfma_f32_16x16x32_bf16 v[32:35], v[164:167], v[188:191], v[32:35]
	v_mfma_f32_16x16x32_bf16 v[24:27], v[172:175], v[188:191], v[24:27]
	v_mfma_f32_16x16x32_bf16 v[16:19], v[164:167], v[196:199], v[16:19]
	v_mfma_f32_16x16x32_bf16 v[8:11], v[172:175], v[196:199], v[8:11]
	v_mfma_f32_16x16x32_bf16 v[4:7], v[164:167], v[204:207], v[4:7]
	v_mfma_f32_16x16x32_bf16 v[0:3], v[172:175], v[204:207], v[0:3]
	s_setprio 0
	s_setprio 1
	v_mfma_f32_16x16x32_bf16 v[48:51], v[168:171], v[184:187], v[48:51]
	v_mfma_f32_16x16x32_bf16 v[40:43], v[176:179], v[184:187], v[40:43]
	v_mfma_f32_16x16x32_bf16 v[32:35], v[168:171], v[192:195], v[32:35]
	v_mfma_f32_16x16x32_bf16 v[24:27], v[176:179], v[192:195], v[24:27]
	v_mfma_f32_16x16x32_bf16 v[16:19], v[168:171], v[200:203], v[16:19]
	v_mfma_f32_16x16x32_bf16 v[8:11], v[176:179], v[200:203], v[8:11]
	v_mfma_f32_16x16x32_bf16 v[4:7], v[168:171], v[210:213], v[4:7]
	v_mfma_f32_16x16x32_bf16 v[0:3], v[176:179], v[210:213], v[0:3]
	s_setprio 0
	s_barrier
	s_movk_i32 s38, 0x100
	s_andn2_b64 vcc, exec, s[8:9]
	s_mov_b64 s[4:5], -1
	s_mov_b64 s[8:9], 0
	s_cbranch_vccz .LBB0_417
	s_and_b64 vcc, exec, s[16:17]
	s_cbranch_vccz .LBB0_420
	s_barrier

; #define PG8_STAGE(bufoff, gbase, voff) do { _Pragma("unroll") for (int _i = 0; _i < 2; ++_i) \
;         __builtin_amdgcn_global_load_lds((const unsigned*)((const char*)(gbase) + (voff)[_i]), (LAS unsigned*)(lds + (bufoff) + ldsw + _i * 8192), 16, 0, 0); } while (0)
; #define PG8_LDA(dst, b, h) do { _Pragma("unroll") for (int m = 0; m < 4; ++m) _Pragma("unroll") for (int k = 0; k < 2; ++k) dst[m][k] = *(const LAS bf16x8*)(lds + PG8_SA(b, h) + aoff + m * 2048 + k * 1024); } while (0)
; #define PG8_LDB(dst, b, h) do { _Pragma("unroll") for (int n = 0; n < 2; ++n) _Pragma("unroll") for (int k = 0; k < 2; ++k) dst[n][k] = *(const LAS bf16x8*)(lds + PG8_SB(b, h) + boff + n * 2048 + k * 1024); } while (0)
; #define PG8_MMA(ai, bj, At, Bt) do { __builtin_amdgcn_s_setprio(1); _Pragma("unroll") for (int m = 0; m < 4; ++m) _Pragma("unroll") for (int n = 0; n < 2; ++n) _Pragma("unroll") for (int k = 0; k < 2; ++k) \
;         acc[ai][bj][m][n] = __builtin_amdgcn_mfma_f32_16x16x32_bf16(Bt[n][k], At[m][k], acc[ai][bj][m][n], 0, 0, 0); __builtin_amdgcn_s_setprio(0); } while (0)
; #define PG8_WAIT_V(n) asm volatile("s_waitcnt vmcnt(" #n ")" ::: "memory")
; #define PG8_WAIT_L(n) asm volatile("s_waitcnt lgkmcnt(" #n ")" ::: "memory")
; #define PG8_BAR __builtin_amdgcn_s_barrier()
; #define PG8_SCHED __builtin_amdgcn_sched_barrier(0)
; template <class Epi, class Sched>
; __device__ __forceinline__ void gemm_phase(LAS unsigned char* lds, const Gemm g, const Sched& S, const Epi& E, const int wave_s) {
;     ...
;             const bool last = (t == nt - 2);
;             const char* a1 = cA + (size_t)(t + 1) * kstep;
;             const char* a2 = last ? nA : cA + (size_t)(t + 2) * kstep; const char* b2 = last ? nB : cB + (size_t)(t + 2) * kstep;
;             const char* a3 = a2 + kstep; const char* b3 = b2 + kstep;
;             PG8_LDB(B0, 0, 0); PG8_LDB(B1, 0, 1); PG8_SCHED; PG8_LDA(At, 0, 0); PG8_STAGE(PG8_SA(1, 1), a1 + hstepA, voffA);
;             PG8_WAIT_V(8); PG8_WAIT_L(0); PG8_BAR; PG8_MMA(0, 0, At, B0); PG8_MMA(0, 1, At, B1); PG8_BAR; PG8_SCHED;
;             PG8_LDA(At, 0, 1); PG8_STAGE(PG8_SB(0, 0), b2, voffB); PG8_STAGE(PG8_SB(0, 1), b2 + hstepB, voffB); PG8_STAGE(PG8_SA(0, 0), a2, voffA);
;             PG8_WAIT_V(8); PG8_WAIT_L(0); PG8_BAR; PG8_MMA(1, 0, At, B0); PG8_MMA(1, 1, At, B1); PG8_BAR; PG8_SCHED;
.LBB0_860:
	ds_read_b128 v[100:103], v212
	ds_read_b128 v[108:111], v212 offset:1024
	ds_read_b128 v[136:139], v212 offset:2048
	ds_read_b128 v[140:143], v212 offset:3072
	ds_read_b128 v[144:147], v213
	ds_read_b128 v[148:151], v213 offset:1024
	ds_read_b128 v[152:155], v213 offset:2048
	ds_read_b128 v[156:159], v213 offset:3072
	s_add_u32 s4, s40, 0xfffc0080
	s_addc_u32 s5, s41, -1
	s_cmp_eq_u32 s54, 12
	s_cselect_b32 s43, s9, s5
	s_cselect_b32 s42, s27, s4
	s_cselect_b32 s5, s29, s53
	s_cselect_b32 s4, s31, s39
	v_lshl_add_u64 v[206:207], s[40:41], 0, v[178:179]
	s_add_i32 m0, s3, 0xc000
	ds_read_b128 v[160:163], v214
	ds_read_b128 v[164:167], v214 offset:1024
	ds_read_b128 v[186:189], v214 offset:2048
	ds_read_b128 v[190:193], v214 offset:3072
	ds_read_b128 v[194:197], v214 offset:4096
	ds_read_b128 v[198:201], v214 offset:5120
	ds_read_b128 v[202:205], v214 offset:6144
	ds_read_b128 v[216:219], v214 offset:7168
	global_load_lds_dwordx4 v[206:207], off
	v_lshl_add_u64 v[206:207], s[40:41], 0, v[180:181]
	s_add_i32 m0, s3, 0xe000
	s_nop 0
	global_load_lds_dwordx4 v[206:207], off
	s_waitcnt vmcnt(8) lgkmcnt(0)
	s_barrier
	s_setprio 1
	v_mfma_f32_16x16x32_bf16 v[132:135], v[100:103], v[160:163], v[132:135]
	v_mfma_f32_16x16x32_bf16 v[128:131], v[136:139], v[160:163], v[128:131]
	v_mfma_f32_16x16x32_bf16 v[124:127], v[100:103], v[186:189], v[124:127]
	v_mfma_f32_16x16x32_bf16 v[120:123], v[136:139], v[186:189], v[120:123]
	v_mfma_f32_16x16x32_bf16 v[116:119], v[100:103], v[194:197], v[116:119]
	v_mfma_f32_16x16x32_bf16 v[112:115], v[136:139], v[194:197], v[112:115]
	v_mfma_f32_16x16x32_bf16 v[104:107], v[100:103], v[202:205], v[104:107]
	v_mfma_f32_16x16x32_bf16 v[96:99], v[136:139], v[202:205], v[96:99]
	s_setprio 0
	s_setprio 1
	v_mfma_f32_16x16x32_bf16 v[132:135], v[108:111], v[164:167], v[132:135]
	v_mfma_f32_16x16x32_bf16 v[128:131], v[140:143], v[164:167], v[128:131]
	v_mfma_f32_16x16x32_bf16 v[124:127], v[108:111], v[190:193], v[124:127]
	v_mfma_f32_16x16x32_bf16 v[120:123], v[140:143], v[190:193], v[120:123]
	v_mfma_f32_16x16x32_bf16 v[116:119], v[108:111], v[198:201], v[116:119]
	v_mfma_f32_16x16x32_bf16 v[112:115], v[140:143], v[198:201], v[112:115]
	v_mfma_f32_16x16x32_bf16 v[104:107], v[108:111], v[216:219], v[104:107]
	v_mfma_f32_16x16x32_bf16 v[96:99], v[140:143], v[216:219], v[96:99]
	s_setprio 0
	s_setprio 1
	v_mfma_f32_16x16x32_bf16 v[60:63], v[144:147], v[160:163], v[60:63]
	v_mfma_f32_16x16x32_bf16 v[56:59], v[152:155], v[160:163], v[56:59]
	v_mfma_f32_16x16x32_bf16 v[52:55], v[144:147], v[186:189], v[52:55]
	v_mfma_f32_16x16x32_bf16 v[48:51], v[152:155], v[186:189], v[48:51]
	v_mfma_f32_16x16x32_bf16 v[44:47], v[144:147], v[194:197], v[44:47]
	v_mfma_f32_16x16x32_bf16 v[40:43], v[152:155], v[194:197], v[40:43]
	v_mfma_f32_16x16x32_bf16 v[36:39], v[144:147], v[202:205], v[36:39]
	v_mfma_f32_16x16x32_bf16 v[32:35], v[152:155], v[202:205], v[32:35]
	s_setprio 0
	s_setprio 1
	v_mfma_f32_16x16x32_bf16 v[60:63], v[148:151], v[164:167], v[60:63]
	v_mfma_f32_16x16x32_bf16 v[56:59], v[156:159], v[164:167], v[56:59]
	v_mfma_f32_16x16x32_bf16 v[52:55], v[148:151], v[190:193], v[52:55]
	v_mfma_f32_16x16x32_bf16 v[48:51], v[156:159], v[190:193], v[48:51]
	v_mfma_f32_16x16x32_bf16 v[44:47], v[148:151], v[198:201], v[44:47]
	v_mfma_f32_16x16x32_bf16 v[40:43], v[156:159], v[198:201], v[40:43]
	v_mfma_f32_16x16x32_bf16 v[36:39], v[148:151], v[216:219], v[36:39]
	v_mfma_f32_16x16x32_bf16 v[32:35], v[156:159], v[216:219], v[32:35]
	s_setprio 0
	s_barrier
	s_add_i32 s55, s50, s81
	v_lshl_add_u64 v[206:207], s[4:5], 0, v[170:171]
	s_mov_b32 m0, s55
	ds_read_b128 v[160:163], v214 offset:16384
	ds_read_b128 v[164:167], v214 offset:17408
	ds_read_b128 v[186:189], v214 offset:18432
	ds_read_b128 v[190:193], v214 offset:19456
	ds_read_b128 v[194:197], v214 offset:20480
	ds_read_b128 v[198:201], v214 offset:21504
	ds_read_b128 v[202:205], v214 offset:22528
	ds_read_b128 v[216:219], v214 offset:23552
	global_load_lds_dwordx4 v[206:207], off
	s_add_i32 m0, s55, 0x2000
	s_add_u32 s56, s4, 0x40000
	v_lshl_add_u64 v[220:221], s[4:5], 0, v[174:175]
	s_addc_u32 s57, s5, 0
	s_add_i32 s55, s51, s81
	global_load_lds_dwordx4 v[220:221], off
	v_lshl_add_u64 v[222:223], s[56:57], 0, v[170:171]
	s_mov_b32 m0, s55
	v_lshl_add_u64 v[224:225], s[42:43], 0, v[172:173]
	global_load_lds_dwordx4 v[222:223], off
	v_lshl_add_u64 v[222:223], s[56:57], 0, v[174:175]
	s_add_i32 m0, s55, 0x2000
	s_nop 0
	global_load_lds_dwordx4 v[222:223], off
	v_lshl_add_u64 v[222:223], s[42:43], 0, v[168:169]
	s_mov_b32 m0, s3
	s_nop 0
	global_load_lds_dwordx4 v[222:223], off
	s_mov_b32 m0, s33
	s_nop 0
	global_load_lds_dwordx4 v[224:225], off
	s_waitcnt vmcnt(8) lgkmcnt(0)
	s_barrier
; #define PG8_STAGE(bufoff, gbase, voff) do { _Pragma("unroll") for (int _i = 0; _i < 2; ++_i) \
;         __builtin_amdgcn_global_load_lds((const unsigned*)((const char*)(gbase) + (voff)[_i]), (LAS unsigned*)(lds + (bufoff) + ldsw + _i * 8192), 16, 0, 0); } while (0)
; #define PG8_LDA(dst, b, h) do { _Pragma("unroll") for (int m = 0; m < 4; ++m) _Pragma("unroll") for (int k = 0; k < 2; ++k) dst[m][k] = *(const LAS bf16x8*)(lds + PG8_SA(b, h) + aoff + m * 2048 + k * 1024); } while (0)
; #define PG8_LDB(dst, b, h) do { _Pragma("unroll") for (int n = 0; n < 2; ++n) _Pragma("unroll") for (int k = 0; k < 2; ++k) dst[n][k] = *(const LAS bf16x8*)(lds + PG8_SB(b, h) + boff + n * 2048 + k * 1024); } while (0)
; #define PG8_MMA(ai, bj, At, Bt) do { __builtin_amdgcn_s_setprio(1); _Pragma("unroll") for (int m = 0; m < 4; ++m) _Pragma("unroll") for (int n = 0; n < 2; ++n) _Pragma("unroll") for (int k = 0; k < 2; ++k) \
;         acc[ai][bj][m][n] = __builtin_amdgcn_mfma_f32_16x16x32_bf16(Bt[n][k], At[m][k], acc[ai][bj][m][n], 0, 0, 0); __builtin_amdgcn_s_setprio(0); } while (0)
; #define PG8_WAIT_V(n) asm volatile("s_waitcnt vmcnt(" #n ")" ::: "memory")
; #define PG8_WAIT_L(n) asm volatile("s_waitcnt lgkmcnt(" #n ")" ::: "memory")
; #define PG8_BAR __builtin_amdgcn_s_barrier()
; #define PG8_SCHED __builtin_amdgcn_sched_barrier(0)
; template <class Epi, class Sched>
; __device__ __forceinline__ void gemm_phase(LAS unsigned char* lds, const Gemm g, const Sched& S, const Epi& E, const int wave_s) {
;     ...
;             PG8_WAIT_V(8); PG8_WAIT_L(0); PG8_BAR; PG8_MMA(1, 0, At, B0); PG8_MMA(1, 1, At, B1); PG8_BAR; PG8_SCHED;
;             PG8_LDB(B0, 1, 0); PG8_LDB(B1, 1, 1); PG8_SCHED; PG8_LDA(At, 1, 0); PG8_STAGE(PG8_SA(0, 1), a2 + hstepA, voffA);
;             PG8_WAIT_V(8); PG8_WAIT_L(0); PG8_BAR; PG8_MMA(0, 0, At, B0); PG8_MMA(0, 1, At, B1); PG8_BAR; PG8_SCHED;
	s_setprio 1
	v_mfma_f32_16x16x32_bf16 v[92:95], v[100:103], v[160:163], v[92:95]
	v_mfma_f32_16x16x32_bf16 v[88:91], v[136:139], v[160:163], v[88:91]
	v_mfma_f32_16x16x32_bf16 v[84:87], v[100:103], v[186:189], v[84:87]
	v_mfma_f32_16x16x32_bf16 v[80:83], v[136:139], v[186:189], v[80:83]
	v_mfma_f32_16x16x32_bf16 v[76:79], v[100:103], v[194:197], v[76:79]
	v_mfma_f32_16x16x32_bf16 v[72:75], v[136:139], v[194:197], v[72:75]
	v_mfma_f32_16x16x32_bf16 v[68:71], v[100:103], v[202:205], v[68:71]
	v_mfma_f32_16x16x32_bf16 v[64:67], v[136:139], v[202:205], v[64:67]
	s_setprio 0
	s_setprio 1
	v_mfma_f32_16x16x32_bf16 v[92:95], v[108:111], v[164:167], v[92:95]
	v_mfma_f32_16x16x32_bf16 v[88:91], v[140:143], v[164:167], v[88:91]
	v_mfma_f32_16x16x32_bf16 v[84:87], v[108:111], v[190:193], v[84:87]
	v_mfma_f32_16x16x32_bf16 v[80:83], v[140:143], v[190:193], v[80:83]
	v_mfma_f32_16x16x32_bf16 v[76:79], v[108:111], v[198:201], v[76:79]
	v_mfma_f32_16x16x32_bf16 v[72:75], v[140:143], v[198:201], v[72:75]
	v_mfma_f32_16x16x32_bf16 v[68:71], v[108:111], v[216:219], v[68:71]
	v_mfma_f32_16x16x32_bf16 v[64:67], v[140:143], v[216:219], v[64:67]
	s_setprio 0
	s_setprio 1
	v_mfma_f32_16x16x32_bf16 v[28:31], v[144:147], v[160:163], v[28:31]
	v_mfma_f32_16x16x32_bf16 v[24:27], v[152:155], v[160:163], v[24:27]
	v_mfma_f32_16x16x32_bf16 v[20:23], v[144:147], v[186:189], v[20:23]
	v_mfma_f32_16x16x32_bf16 v[16:19], v[152:155], v[186:189], v[16:19]
	v_mfma_f32_16x16x32_bf16 v[12:15], v[144:147], v[194:197], v[12:15]
	v_mfma_f32_16x16x32_bf16 v[8:11], v[152:155], v[194:197], v[8:11]
	v_mfma_f32_16x16x32_bf16 v[4:7], v[144:147], v[202:205], v[4:7]
	v_mfma_f32_16x16x32_bf16 v[0:3], v[152:155], v[202:205], v[0:3]
	s_setprio 0
	s_setprio 1
	v_mfma_f32_16x16x32_bf16 v[28:31], v[148:151], v[164:167], v[28:31]
	v_mfma_f32_16x16x32_bf16 v[24:27], v[156:159], v[164:167], v[24:27]
	v_mfma_f32_16x16x32_bf16 v[20:23], v[148:151], v[190:193], v[20:23]
	v_mfma_f32_16x16x32_bf16 v[16:19], v[156:159], v[190:193], v[16:19]
	v_mfma_f32_16x16x32_bf16 v[12:15], v[148:151], v[198:201], v[12:15]
	v_mfma_f32_16x16x32_bf16 v[8:11], v[156:159], v[198:201], v[8:11]
	v_mfma_f32_16x16x32_bf16 v[4:7], v[148:151], v[216:219], v[4:7]
	v_mfma_f32_16x16x32_bf16 v[0:3], v[156:159], v[216:219], v[0:3]
	s_setprio 0
	s_barrier
	s_add_i32 s55, 0, 0x18000
	s_add_i32 s56, 0, 0x1c000
	v_add_u32_e32 v140, s55, v210
	v_add_u32_e32 v156, s56, v210
	ds_read_b128 v[100:103], v140
	ds_read_b128 v[108:111], v140 offset:1024
	ds_read_b128 v[136:139], v140 offset:2048
	ds_read_b128 v[140:143], v140 offset:3072
	ds_read_b128 v[144:147], v156
	ds_read_b128 v[148:151], v156 offset:1024
	ds_read_b128 v[152:155], v156 offset:2048
	ds_read_b128 v[156:159], v156 offset:3072
	s_add_u32 s42, s42, 0x40000
	s_addc_u32 s43, s43, 0
	s_mov_b32 m0, s44
	v_lshl_add_u64 v[226:227], s[42:43], 0, v[168:169]
	ds_read_b128 v[160:163], v214 offset:32768
	ds_read_b128 v[164:167], v214 offset:33792
	ds_read_b128 v[186:189], v214 offset:34816
	ds_read_b128 v[190:193], v214 offset:35840
	ds_read_b128 v[194:197], v214 offset:36864
	ds_read_b128 v[198:201], v214 offset:37888
	ds_read_b128 v[202:205], v214 offset:38912
	ds_read_b128 v[216:219], v214 offset:39936
	global_load_lds_dwordx4 v[226:227], off
	v_lshl_add_u64 v[226:227], s[42:43], 0, v[172:173]
	s_mov_b32 m0, s45
	s_nop 0
	global_load_lds_dwordx4 v[226:227], off
	s_waitcnt vmcnt(8) lgkmcnt(0)
	s_barrier
	s_setprio 1
	v_mfma_f32_16x16x32_bf16 v[132:135], v[100:103], v[160:163], v[132:135]
	v_mfma_f32_16x16x32_bf16 v[128:131], v[136:139], v[160:163], v[128:131]
	v_mfma_f32_16x16x32_bf16 v[124:127], v[100:103], v[186:189], v[124:127]
	v_mfma_f32_16x16x32_bf16 v[120:123], v[136:139], v[186:189], v[120:123]
	v_mfma_f32_16x16x32_bf16 v[116:119], v[100:103], v[194:197], v[116:119]
	v_mfma_f32_16x16x32_bf16 v[112:115], v[136:139], v[194:197], v[112:115]
	v_mfma_f32_16x16x32_bf16 v[104:107], v[100:103], v[202:205], v[104:107]
	v_mfma_f32_16x16x32_bf16 v[96:99], v[136:139], v[202:205], v[96:99]
	s_setprio 0
	s_setprio 1
	v_mfma_f32_16x16x32_bf16 v[132:135], v[108:111], v[164:167], v[132:135]
	v_mfma_f32_16x16x32_bf16 v[128:131], v[140:143], v[164:167], v[128:131]
	v_mfma_f32_16x16x32_bf16 v[124:127], v[108:111], v[190:193], v[124:127]
	v_mfma_f32_16x16x32_bf16 v[120:123], v[140:143], v[190:193], v[120:123]
	v_mfma_f32_16x16x32_bf16 v[116:119], v[108:111], v[198:201], v[116:119]
	v_mfma_f32_16x16x32_bf16 v[112:115], v[140:143], v[198:201], v[112:115]
	v_mfma_f32_16x16x32_bf16 v[104:107], v[108:111], v[216:219], v[104:107]
	v_mfma_f32_16x16x32_bf16 v[96:99], v[140:143], v[216:219], v[96:99]
	s_setprio 0
	s_setprio 1
	v_mfma_f32_16x16x32_bf16 v[60:63], v[144:147], v[160:163], v[60:63]
	v_mfma_f32_16x16x32_bf16 v[56:59], v[152:155], v[160:163], v[56:59]
	v_mfma_f32_16x16x32_bf16 v[52:55], v[144:147], v[186:189], v[52:55]
	v_mfma_f32_16x16x32_bf16 v[48:51], v[152:155], v[186:189], v[48:51]
	v_mfma_f32_16x16x32_bf16 v[44:47], v[144:147], v[194:197], v[44:47]
	v_mfma_f32_16x16x32_bf16 v[40:43], v[152:155], v[194:197], v[40:43]
	v_mfma_f32_16x16x32_bf16 v[36:39], v[144:147], v[202:205], v[36:39]
	v_mfma_f32_16x16x32_bf16 v[32:35], v[152:155], v[202:205], v[32:35]
	s_setprio 0
	s_setprio 1
	v_mfma_f32_16x16x32_bf16 v[60:63], v[148:151], v[164:167], v[60:63]
	v_mfma_f32_16x16x32_bf16 v[56:59], v[156:159], v[164:167], v[56:59]
	v_mfma_f32_16x16x32_bf16 v[52:55], v[148:151], v[190:193], v[52:55]
	v_mfma_f32_16x16x32_bf16 v[48:51], v[156:159], v[190:193], v[48:51]
	v_mfma_f32_16x16x32_bf16 v[44:47], v[148:151], v[198:201], v[44:47]
	v_mfma_f32_16x16x32_bf16 v[40:43], v[156:159], v[198:201], v[40:43]
	v_mfma_f32_16x16x32_bf16 v[36:39], v[148:151], v[216:219], v[36:39]
	v_mfma_f32_16x16x32_bf16 v[32:35], v[156:159], v[216:219], v[32:35]
	s_setprio 0
	s_barrier
; #define PG8_STAGE(bufoff, gbase, voff) do { _Pragma("unroll") for (int _i = 0; _i < 2; ++_i) \
;         __builtin_amdgcn_global_load_lds((const unsigned*)((const char*)(gbase) + (voff)[_i]), (LAS unsigned*)(lds + (bufoff) + ldsw + _i * 8192), 16, 0, 0); } while (0)
; #define PG8_LDA(dst, b, h) do { _Pragma("unroll") for (int m = 0; m < 4; ++m) _Pragma("unroll") for (int k = 0; k < 2; ++k) dst[m][k] = *(const LAS bf16x8*)(lds + PG8_SA(b, h) + aoff + m * 2048 + k * 1024); } while (0)
; #define PG8_MMA(ai, bj, At, Bt) do { __builtin_amdgcn_s_setprio(1); _Pragma("unroll") for (int m = 0; m < 4; ++m) _Pragma("unroll") for (int n = 0; n < 2; ++n) _Pragma("unroll") for (int k = 0; k < 2; ++k) \
;         acc[ai][bj][m][n] = __builtin_amdgcn_mfma_f32_16x16x32_bf16(Bt[n][k], At[m][k], acc[ai][bj][m][n], 0, 0, 0); __builtin_amdgcn_s_setprio(0); } while (0)
; #define PG8_WAIT_V(n) asm volatile("s_waitcnt vmcnt(" #n ")" ::: "memory")
; #define PG8_WAIT_L(n) asm volatile("s_waitcnt lgkmcnt(" #n ")" ::: "memory")
; #define PG8_BAR __builtin_amdgcn_s_barrier()
; #define PG8_SCHED __builtin_amdgcn_sched_barrier(0)
; template <class Epi, class Sched>
; __device__ __forceinline__ void gemm_phase(LAS unsigned char* lds, const Gemm g, const Sched& S, const Epi& E, const int wave_s) {
;     ...
;             PG8_LDA(At, 1, 1); PG8_STAGE(PG8_SB(1, 0), b3, voffB); PG8_STAGE(PG8_SB(1, 1), b3 + hstepB, voffB); PG8_STAGE(PG8_SA(1, 0), a3, voffA);
;             PG8_WAIT_V(8); PG8_WAIT_L(0); PG8_BAR; PG8_MMA(1, 0, At, B0); PG8_MMA(1, 1, At, B1); PG8_BAR; PG8_SCHED;
;         }
	s_add_i32 s42, s55, s81
	v_lshl_add_u64 v[206:207], v[206:207], 0, s[22:23]
	s_mov_b32 m0, s42
	ds_read_b128 v[160:163], v214 offset:49152
	ds_read_b128 v[164:167], v214 offset:50176
	ds_read_b128 v[186:189], v214 offset:51200
	ds_read_b128 v[190:193], v214 offset:52224
	ds_read_b128 v[194:197], v214 offset:53248
	ds_read_b128 v[198:201], v214 offset:54272
	ds_read_b128 v[202:205], v214 offset:55296
	ds_read_b128 v[216:219], v214 offset:56320
	global_load_lds_dwordx4 v[206:207], off
	s_add_i32 m0, s42, 0x2000
	s_add_u32 s4, s4, 0x40080
	v_lshl_add_u64 v[206:207], v[220:221], 0, s[22:23]
	s_addc_u32 s5, s5, 0
	s_add_i32 s42, s56, s81
	global_load_lds_dwordx4 v[206:207], off
	v_lshl_add_u64 v[206:207], s[4:5], 0, v[170:171]
	s_mov_b32 m0, s42
	s_nop 0
	global_load_lds_dwordx4 v[206:207], off
	v_lshl_add_u64 v[206:207], s[4:5], 0, v[174:175]
	s_add_i32 m0, s42, 0x2000
	s_nop 0
	global_load_lds_dwordx4 v[206:207], off
	v_lshl_add_u64 v[206:207], v[222:223], 0, s[22:23]
	s_mov_b32 m0, s47
	s_nop 0
	global_load_lds_dwordx4 v[206:207], off
	v_lshl_add_u64 v[206:207], v[224:225], 0, s[22:23]
	s_mov_b32 m0, s48
	s_nop 0
	global_load_lds_dwordx4 v[206:207], off
	s_waitcnt vmcnt(8) lgkmcnt(0)
	s_barrier
	s_setprio 1
	v_mfma_f32_16x16x32_bf16 v[92:95], v[100:103], v[160:163], v[92:95]
	v_mfma_f32_16x16x32_bf16 v[88:91], v[136:139], v[160:163], v[88:91]
	v_mfma_f32_16x16x32_bf16 v[84:87], v[100:103], v[186:189], v[84:87]
	v_mfma_f32_16x16x32_bf16 v[80:83], v[136:139], v[186:189], v[80:83]
	v_mfma_f32_16x16x32_bf16 v[76:79], v[100:103], v[194:197], v[76:79]
	v_mfma_f32_16x16x32_bf16 v[72:75], v[136:139], v[194:197], v[72:75]
	v_mfma_f32_16x16x32_bf16 v[68:71], v[100:103], v[202:205], v[68:71]
	v_mfma_f32_16x16x32_bf16 v[64:67], v[136:139], v[202:205], v[64:67]
	s_setprio 0
	s_setprio 1
	v_mfma_f32_16x16x32_bf16 v[92:95], v[108:111], v[164:167], v[92:95]
	v_mfma_f32_16x16x32_bf16 v[88:91], v[140:143], v[164:167], v[88:91]
	v_mfma_f32_16x16x32_bf16 v[84:87], v[108:111], v[190:193], v[84:87]
	v_mfma_f32_16x16x32_bf16 v[80:83], v[140:143], v[190:193], v[80:83]
	v_mfma_f32_16x16x32_bf16 v[76:79], v[108:111], v[198:201], v[76:79]
	v_mfma_f32_16x16x32_bf16 v[72:75], v[140:143], v[198:201], v[72:75]
	v_mfma_f32_16x16x32_bf16 v[68:71], v[108:111], v[216:219], v[68:71]
	v_mfma_f32_16x16x32_bf16 v[64:67], v[140:143], v[216:219], v[64:67]
	s_setprio 0
	s_setprio 1
	v_mfma_f32_16x16x32_bf16 v[28:31], v[144:147], v[160:163], v[28:31]
	v_mfma_f32_16x16x32_bf16 v[24:27], v[152:155], v[160:163], v[24:27]
	v_mfma_f32_16x16x32_bf16 v[20:23], v[144:147], v[186:189], v[20:23]
	v_mfma_f32_16x16x32_bf16 v[16:19], v[152:155], v[186:189], v[16:19]
	v_mfma_f32_16x16x32_bf16 v[12:15], v[144:147], v[194:197], v[12:15]
	v_mfma_f32_16x16x32_bf16 v[8:11], v[152:155], v[194:197], v[8:11]
	v_mfma_f32_16x16x32_bf16 v[4:7], v[144:147], v[202:205], v[4:7]
	v_mfma_f32_16x16x32_bf16 v[0:3], v[152:155], v[202:205], v[0:3]
	s_setprio 0
	s_setprio 1
	v_mfma_f32_16x16x32_bf16 v[28:31], v[148:151], v[164:167], v[28:31]
	v_mfma_f32_16x16x32_bf16 v[24:27], v[156:159], v[164:167], v[24:27]
	v_mfma_f32_16x16x32_bf16 v[20:23], v[148:151], v[190:193], v[20:23]
	v_mfma_f32_16x16x32_bf16 v[16:19], v[156:159], v[190:193], v[16:19]
	v_mfma_f32_16x16x32_bf16 v[12:15], v[148:151], v[198:201], v[12:15]
	v_mfma_f32_16x16x32_bf16 v[8:11], v[156:159], v[198:201], v[8:11]
	v_mfma_f32_16x16x32_bf16 v[4:7], v[148:151], v[216:219], v[4:7]
	v_mfma_f32_16x16x32_bf16 v[0:3], v[156:159], v[216:219], v[0:3]
	s_setprio 0
	s_barrier
	s_add_i32 s54, s54, 2
	s_add_u32 s40, s40, 0x100
	s_addc_u32 s41, s41, 0
	s_add_u32 s39, s39, 0x100
	s_addc_u32 s53, s53, 0
	s_cmp_gt_u32 s54, 13
	s_cbranch_scc0 .LBB0_860
	s_and_b64 vcc, exec, s[24:25]
	s_cbranch_vccz .LBB0_863
	s_barrier

; #define PG8_STAGE(bufoff, gbase, voff) do { _Pragma("unroll") for (int _i = 0; _i < 2; ++_i) \
;         __builtin_amdgcn_global_load_lds((const unsigned*)((const char*)(gbase) + (voff)[_i]), (LAS unsigned*)(lds + (bufoff) + ldsw + _i * 8192), 16, 0, 0); } while (0)
; #define PG8_LDA(dst, b, h) do { _Pragma("unroll") for (int m = 0; m < 4; ++m) _Pragma("unroll") for (int k = 0; k < 2; ++k) dst[m][k] = *(const LAS bf16x8*)(lds + PG8_SA(b, h) + aoff + m * 2048 + k * 1024); } while (0)
; #define PG8_LDB(dst, b, h) do { _Pragma("unroll") for (int n = 0; n < 2; ++n) _Pragma("unroll") for (int k = 0; k < 2; ++k) dst[n][k] = *(const LAS bf16x8*)(lds + PG8_SB(b, h) + boff + n * 2048 + k * 1024); } while (0)
; #define PG8_MMA(ai, bj, At, Bt) do { __builtin_amdgcn_s_setprio(1); _Pragma("unroll") for (int m = 0; m < 4; ++m) _Pragma("unroll") for (int n = 0; n < 2; ++n) _Pragma("unroll") for (int k = 0; k < 2; ++k) \
;         acc[ai][bj][m][n] = __builtin_amdgcn_mfma_f32_16x16x32_bf16(Bt[n][k], At[m][k], acc[ai][bj][m][n], 0, 0, 0); __builtin_amdgcn_s_setprio(0); } while (0)
; #define PG8_WAIT_V(n) asm volatile("s_waitcnt vmcnt(" #n ")" ::: "memory")
; #define PG8_WAIT_L(n) asm volatile("s_waitcnt lgkmcnt(" #n ")" ::: "memory")
; #define PG8_BAR __builtin_amdgcn_s_barrier()
; #define PG8_SCHED __builtin_amdgcn_sched_barrier(0)
; template <class Epi, class Sched>
; __device__ __forceinline__ void gemm_phase(LAS unsigned char* lds, const Gemm g, const Sched& S, const Epi& E, const int wave_s) {
;     ...
;             const bool last = (t == nt - 2);
;             const char* a1 = cA + (size_t)(t + 1) * kstep;
;             const char* a2 = last ? nA : cA + (size_t)(t + 2) * kstep; const char* b2 = last ? nB : cB + (size_t)(t + 2) * kstep;
;             const char* a3 = a2 + kstep; const char* b3 = b2 + kstep;
;             PG8_LDB(B0, 0, 0); PG8_LDB(B1, 0, 1); PG8_SCHED; PG8_LDA(At, 0, 0); PG8_STAGE(PG8_SA(1, 1), a1 + hstepA, voffA);
;             PG8_WAIT_V(8); PG8_WAIT_L(0); PG8_BAR; PG8_MMA(0, 0, At, B0); PG8_MMA(0, 1, At, B1); PG8_BAR; PG8_SCHED;
;             PG8_LDA(At, 0, 1); PG8_STAGE(PG8_SB(0, 0), b2, voffB); PG8_STAGE(PG8_SB(0, 1), b2 + hstepB, voffB); PG8_STAGE(PG8_SA(0, 0), a2, voffA);
;             PG8_WAIT_V(8); PG8_WAIT_L(0); PG8_BAR; PG8_MMA(1, 0, At, B0); PG8_MMA(1, 1, At, B1); PG8_BAR; PG8_SCHED;
.LBB0_1024:
	s_add_u32 s48, s64, s46
	s_addc_u32 s49, s65, s47
	s_add_u32 s48, s48, 0x99a5200
	s_addc_u32 s49, s49, 0
	s_add_u32 s73, s70, s46
	s_addc_u32 s74, s71, s47
	s_add_i32 s75, 0, 0x10000
	s_cmpk_eq_i32 s46, 0x700
	s_cselect_b32 s51, s11, s49
	s_cselect_b32 s50, s10, s48
	v_add_u32_e32 v128, s75, v178
	s_cselect_b32 s49, s68, s74
	s_cselect_b32 s48, s69, s73
	s_add_i32 s73, 0, 0x14000
	ds_read_b128 v[170:173], v128
	ds_read_b128 v[182:185], v128 offset:1024
	ds_read_b128 v[186:189], v128 offset:2048
	ds_read_b128 v[190:193], v128 offset:3072
	v_add_u32_e32 v128, s73, v178
	ds_read_b128 v[194:197], v128
	ds_read_b128 v[198:201], v128 offset:1024
	ds_read_b128 v[202:205], v128 offset:2048
	ds_read_b128 v[206:209], v128 offset:3072
	v_lshl_add_u64 v[242:243], v[166:167], 0, s[46:47]
	s_add_i32 m0, s52, 0xc000
	ds_read_b128 v[210:213], v180
	ds_read_b128 v[214:217], v180 offset:1024
	ds_read_b128 v[218:221], v180 offset:2048
	ds_read_b128 v[222:225], v180 offset:3072
	ds_read_b128 v[226:229], v180 offset:4096
	ds_read_b128 v[230:233], v180 offset:5120
	ds_read_b128 v[234:237], v180 offset:6144
	ds_read_b128 v[238:241], v180 offset:7168
	global_load_lds_dwordx4 v[242:243], off
	v_lshl_add_u64 v[242:243], v[168:169], 0, s[46:47]
	s_add_i32 m0, s52, 0xe000
	s_nop 0
	global_load_lds_dwordx4 v[242:243], off
	s_waitcnt vmcnt(8) lgkmcnt(0)
	s_barrier
	s_setprio 1
	v_mfma_f32_16x16x32_bf16 v[124:127], v[170:173], v[210:213], v[124:127]
	v_mfma_f32_16x16x32_bf16 v[120:123], v[186:189], v[210:213], v[120:123]
	v_mfma_f32_16x16x32_bf16 v[116:119], v[170:173], v[218:221], v[116:119]
	v_mfma_f32_16x16x32_bf16 v[112:115], v[186:189], v[218:221], v[112:115]
	v_mfma_f32_16x16x32_bf16 v[108:111], v[170:173], v[226:229], v[108:111]
	v_mfma_f32_16x16x32_bf16 v[100:103], v[186:189], v[226:229], v[100:103]
	v_mfma_f32_16x16x32_bf16 v[92:95], v[170:173], v[234:237], v[92:95]
	v_mfma_f32_16x16x32_bf16 v[84:87], v[186:189], v[234:237], v[84:87]
	s_setprio 0
	s_setprio 1
	v_mfma_f32_16x16x32_bf16 v[124:127], v[182:185], v[214:217], v[124:127]
	v_mfma_f32_16x16x32_bf16 v[120:123], v[190:193], v[214:217], v[120:123]
	v_mfma_f32_16x16x32_bf16 v[116:119], v[182:185], v[222:225], v[116:119]
	v_mfma_f32_16x16x32_bf16 v[112:115], v[190:193], v[222:225], v[112:115]
	v_mfma_f32_16x16x32_bf16 v[108:111], v[182:185], v[230:233], v[108:111]
	v_mfma_f32_16x16x32_bf16 v[100:103], v[190:193], v[230:233], v[100:103]
	v_mfma_f32_16x16x32_bf16 v[92:95], v[182:185], v[238:241], v[92:95]
	v_mfma_f32_16x16x32_bf16 v[84:87], v[190:193], v[238:241], v[84:87]
	s_setprio 0
	s_setprio 1
	v_mfma_f32_16x16x32_bf16 v[104:107], v[194:197], v[210:213], v[104:107]
	v_mfma_f32_16x16x32_bf16 v[96:99], v[202:205], v[210:213], v[96:99]
	v_mfma_f32_16x16x32_bf16 v[88:91], v[194:197], v[218:221], v[88:91]
	v_mfma_f32_16x16x32_bf16 v[80:83], v[202:205], v[218:221], v[80:83]
	v_mfma_f32_16x16x32_bf16 v[76:79], v[194:197], v[226:229], v[76:79]
	v_mfma_f32_16x16x32_bf16 v[72:75], v[202:205], v[226:229], v[72:75]
	v_mfma_f32_16x16x32_bf16 v[68:71], v[194:197], v[234:237], v[68:71]
	v_mfma_f32_16x16x32_bf16 v[64:67], v[202:205], v[234:237], v[64:67]
	s_setprio 0
	s_setprio 1
	v_mfma_f32_16x16x32_bf16 v[104:107], v[198:201], v[214:217], v[104:107]
	v_mfma_f32_16x16x32_bf16 v[96:99], v[206:209], v[214:217], v[96:99]
	v_mfma_f32_16x16x32_bf16 v[88:91], v[198:201], v[222:225], v[88:91]
	v_mfma_f32_16x16x32_bf16 v[80:83], v[206:209], v[222:225], v[80:83]
	v_mfma_f32_16x16x32_bf16 v[76:79], v[198:201], v[230:233], v[76:79]
	v_mfma_f32_16x16x32_bf16 v[72:75], v[206:209], v[230:233], v[72:75]
	v_mfma_f32_16x16x32_bf16 v[68:71], v[198:201], v[238:241], v[68:71]
	v_mfma_f32_16x16x32_bf16 v[64:67], v[206:209], v[238:241], v[64:67]
	s_setprio 0
	s_barrier
	s_add_i32 s74, s75, s81
	v_lshl_add_u64 v[242:243], s[48:49], 0, v[130:131]
	s_mov_b32 m0, s74
	ds_read_b128 v[210:213], v180 offset:16384
	ds_read_b128 v[214:217], v180 offset:17408
	ds_read_b128 v[218:221], v180 offset:18432
	ds_read_b128 v[222:225], v180 offset:19456
	ds_read_b128 v[226:229], v180 offset:20480
	ds_read_b128 v[230:233], v180 offset:21504
	ds_read_b128 v[234:237], v180 offset:22528
	ds_read_b128 v[238:241], v180 offset:23552
	global_load_lds_dwordx4 v[242:243], off
	s_add_i32 m0, s74, 0x2000
	s_add_u32 s74, s48, 0x40000
	v_lshl_add_u64 v[244:245], s[48:49], 0, v[132:133]
	s_addc_u32 s75, s49, 0
	s_add_i32 s73, s73, s81
	global_load_lds_dwordx4 v[244:245], off
	v_lshl_add_u64 v[246:247], s[74:75], 0, v[130:131]
	s_mov_b32 m0, s73
	v_lshl_add_u64 v[248:249], s[50:51], 0, v[132:133]
	global_load_lds_dwordx4 v[246:247], off
	v_lshl_add_u64 v[246:247], s[74:75], 0, v[132:133]
	s_add_i32 m0, s73, 0x2000
	s_nop 0
	global_load_lds_dwordx4 v[246:247], off
	v_lshl_add_u64 v[246:247], s[50:51], 0, v[130:131]
	s_mov_b32 m0, s52
	s_nop 0
	global_load_lds_dwordx4 v[246:247], off
	s_mov_b32 m0, s57
	s_nop 0
	global_load_lds_dwordx4 v[248:249], off
	s_waitcnt vmcnt(8) lgkmcnt(0)
	s_barrier
; #define PG8_STAGE(bufoff, gbase, voff) do { _Pragma("unroll") for (int _i = 0; _i < 2; ++_i) \
;         __builtin_amdgcn_global_load_lds((const unsigned*)((const char*)(gbase) + (voff)[_i]), (LAS unsigned*)(lds + (bufoff) + ldsw + _i * 8192), 16, 0, 0); } while (0)
; #define PG8_LDA(dst, b, h) do { _Pragma("unroll") for (int m = 0; m < 4; ++m) _Pragma("unroll") for (int k = 0; k < 2; ++k) dst[m][k] = *(const LAS bf16x8*)(lds + PG8_SA(b, h) + aoff + m * 2048 + k * 1024); } while (0)
; #define PG8_LDB(dst, b, h) do { _Pragma("unroll") for (int n = 0; n < 2; ++n) _Pragma("unroll") for (int k = 0; k < 2; ++k) dst[n][k] = *(const LAS bf16x8*)(lds + PG8_SB(b, h) + boff + n * 2048 + k * 1024); } while (0)
; #define PG8_MMA(ai, bj, At, Bt) do { __builtin_amdgcn_s_setprio(1); _Pragma("unroll") for (int m = 0; m < 4; ++m) _Pragma("unroll") for (int n = 0; n < 2; ++n) _Pragma("unroll") for (int k = 0; k < 2; ++k) \
;         acc[ai][bj][m][n] = __builtin_amdgcn_mfma_f32_16x16x32_bf16(Bt[n][k], At[m][k], acc[ai][bj][m][n], 0, 0, 0); __builtin_amdgcn_s_setprio(0); } while (0)
; #define PG8_WAIT_V(n) asm volatile("s_waitcnt vmcnt(" #n ")" ::: "memory")
; #define PG8_WAIT_L(n) asm volatile("s_waitcnt lgkmcnt(" #n ")" ::: "memory")
; #define PG8_BAR __builtin_amdgcn_s_barrier()
; #define PG8_SCHED __builtin_amdgcn_sched_barrier(0)
; template <class Epi, class Sched>
; __device__ __forceinline__ void gemm_phase(LAS unsigned char* lds, const Gemm g, const Sched& S, const Epi& E, const int wave_s) {
;     ...
;             PG8_WAIT_V(8); PG8_WAIT_L(0); PG8_BAR; PG8_MMA(1, 0, At, B0); PG8_MMA(1, 1, At, B1); PG8_BAR; PG8_SCHED;
;             PG8_LDB(B0, 1, 0); PG8_LDB(B1, 1, 1); PG8_SCHED; PG8_LDA(At, 1, 0); PG8_STAGE(PG8_SA(0, 1), a2 + hstepA, voffA);
;             PG8_WAIT_V(8); PG8_WAIT_L(0); PG8_BAR; PG8_MMA(0, 0, At, B0); PG8_MMA(0, 1, At, B1); PG8_BAR; PG8_SCHED;
	s_setprio 1
	v_mfma_f32_16x16x32_bf16 v[60:63], v[170:173], v[210:213], v[60:63]
	v_mfma_f32_16x16x32_bf16 v[56:59], v[186:189], v[210:213], v[56:59]
	v_mfma_f32_16x16x32_bf16 v[52:55], v[170:173], v[218:221], v[52:55]
	v_mfma_f32_16x16x32_bf16 v[48:51], v[186:189], v[218:221], v[48:51]
	v_mfma_f32_16x16x32_bf16 v[44:47], v[170:173], v[226:229], v[44:47]
	v_mfma_f32_16x16x32_bf16 v[36:39], v[186:189], v[226:229], v[36:39]
	v_mfma_f32_16x16x32_bf16 v[28:31], v[170:173], v[234:237], v[28:31]
	v_mfma_f32_16x16x32_bf16 v[20:23], v[186:189], v[234:237], v[20:23]
	s_setprio 0
	s_setprio 1
	v_mfma_f32_16x16x32_bf16 v[60:63], v[182:185], v[214:217], v[60:63]
	v_mfma_f32_16x16x32_bf16 v[56:59], v[190:193], v[214:217], v[56:59]
	v_mfma_f32_16x16x32_bf16 v[52:55], v[182:185], v[222:225], v[52:55]
	v_mfma_f32_16x16x32_bf16 v[48:51], v[190:193], v[222:225], v[48:51]
	v_mfma_f32_16x16x32_bf16 v[44:47], v[182:185], v[230:233], v[44:47]
	v_mfma_f32_16x16x32_bf16 v[36:39], v[190:193], v[230:233], v[36:39]
	v_mfma_f32_16x16x32_bf16 v[28:31], v[182:185], v[238:241], v[28:31]
	v_mfma_f32_16x16x32_bf16 v[20:23], v[190:193], v[238:241], v[20:23]
	s_setprio 0
	s_setprio 1
	v_mfma_f32_16x16x32_bf16 v[40:43], v[194:197], v[210:213], v[40:43]
	v_mfma_f32_16x16x32_bf16 v[32:35], v[202:205], v[210:213], v[32:35]
	v_mfma_f32_16x16x32_bf16 v[24:27], v[194:197], v[218:221], v[24:27]
	v_mfma_f32_16x16x32_bf16 v[16:19], v[202:205], v[218:221], v[16:19]
	v_mfma_f32_16x16x32_bf16 v[12:15], v[194:197], v[226:229], v[12:15]
	v_mfma_f32_16x16x32_bf16 v[8:11], v[202:205], v[226:229], v[8:11]
	v_mfma_f32_16x16x32_bf16 v[4:7], v[194:197], v[234:237], v[4:7]
	v_mfma_f32_16x16x32_bf16 v[0:3], v[202:205], v[234:237], v[0:3]
	s_setprio 0
	s_setprio 1
	v_mfma_f32_16x16x32_bf16 v[40:43], v[198:201], v[214:217], v[40:43]
	v_mfma_f32_16x16x32_bf16 v[32:35], v[206:209], v[214:217], v[32:35]
	v_mfma_f32_16x16x32_bf16 v[24:27], v[198:201], v[222:225], v[24:27]
	v_mfma_f32_16x16x32_bf16 v[16:19], v[206:209], v[222:225], v[16:19]
	v_mfma_f32_16x16x32_bf16 v[12:15], v[198:201], v[230:233], v[12:15]
	v_mfma_f32_16x16x32_bf16 v[8:11], v[206:209], v[230:233], v[8:11]
	v_mfma_f32_16x16x32_bf16 v[4:7], v[198:201], v[238:241], v[4:7]
	v_mfma_f32_16x16x32_bf16 v[0:3], v[206:209], v[238:241], v[0:3]
	s_setprio 0
	s_barrier
	s_add_i32 s73, 0, 0x18000
	v_add_u32_e32 v128, s73, v178
	s_add_i32 s74, 0, 0x1c000
	ds_read_b128 v[170:173], v128
	ds_read_b128 v[182:185], v128 offset:1024
	ds_read_b128 v[186:189], v128 offset:2048
	ds_read_b128 v[190:193], v128 offset:3072
	v_add_u32_e32 v128, s74, v178
	ds_read_b128 v[194:197], v128
	ds_read_b128 v[198:201], v128 offset:1024
	ds_read_b128 v[202:205], v128 offset:2048
	ds_read_b128 v[206:209], v128 offset:3072
	s_add_u32 s50, s50, 0x40000
	s_addc_u32 s51, s51, 0
	s_mov_b32 m0, s58
	v_lshl_add_u64 v[250:251], s[50:51], 0, v[130:131]
	ds_read_b128 v[210:213], v180 offset:32768
	ds_read_b128 v[214:217], v180 offset:33792
	ds_read_b128 v[218:221], v180 offset:34816
	ds_read_b128 v[222:225], v180 offset:35840
	ds_read_b128 v[226:229], v180 offset:36864
	ds_read_b128 v[230:233], v180 offset:37888
	ds_read_b128 v[234:237], v180 offset:38912
	ds_read_b128 v[238:241], v180 offset:39936
	global_load_lds_dwordx4 v[250:251], off
	v_lshl_add_u64 v[250:251], s[50:51], 0, v[132:133]
	s_mov_b32 m0, s59
	s_nop 0
	global_load_lds_dwordx4 v[250:251], off
	s_waitcnt vmcnt(8) lgkmcnt(0)
	s_barrier
	s_setprio 1
	v_mfma_f32_16x16x32_bf16 v[124:127], v[170:173], v[210:213], v[124:127]
	v_mfma_f32_16x16x32_bf16 v[120:123], v[186:189], v[210:213], v[120:123]
	v_mfma_f32_16x16x32_bf16 v[116:119], v[170:173], v[218:221], v[116:119]
	v_mfma_f32_16x16x32_bf16 v[112:115], v[186:189], v[218:221], v[112:115]
	v_mfma_f32_16x16x32_bf16 v[108:111], v[170:173], v[226:229], v[108:111]
	v_mfma_f32_16x16x32_bf16 v[100:103], v[186:189], v[226:229], v[100:103]
	v_mfma_f32_16x16x32_bf16 v[92:95], v[170:173], v[234:237], v[92:95]
	v_mfma_f32_16x16x32_bf16 v[84:87], v[186:189], v[234:237], v[84:87]
	s_setprio 0
	s_setprio 1
	v_mfma_f32_16x16x32_bf16 v[124:127], v[182:185], v[214:217], v[124:127]
	v_mfma_f32_16x16x32_bf16 v[120:123], v[190:193], v[214:217], v[120:123]
	v_mfma_f32_16x16x32_bf16 v[116:119], v[182:185], v[222:225], v[116:119]
	v_mfma_f32_16x16x32_bf16 v[112:115], v[190:193], v[222:225], v[112:115]
	v_mfma_f32_16x16x32_bf16 v[108:111], v[182:185], v[230:233], v[108:111]
	v_mfma_f32_16x16x32_bf16 v[100:103], v[190:193], v[230:233], v[100:103]
	v_mfma_f32_16x16x32_bf16 v[92:95], v[182:185], v[238:241], v[92:95]
	v_mfma_f32_16x16x32_bf16 v[84:87], v[190:193], v[238:241], v[84:87]
	s_setprio 0
	s_setprio 1
	v_mfma_f32_16x16x32_bf16 v[104:107], v[194:197], v[210:213], v[104:107]
	v_mfma_f32_16x16x32_bf16 v[96:99], v[202:205], v[210:213], v[96:99]
	v_mfma_f32_16x16x32_bf16 v[88:91], v[194:197], v[218:221], v[88:91]
	v_mfma_f32_16x16x32_bf16 v[80:83], v[202:205], v[218:221], v[80:83]
	v_mfma_f32_16x16x32_bf16 v[76:79], v[194:197], v[226:229], v[76:79]
	v_mfma_f32_16x16x32_bf16 v[72:75], v[202:205], v[226:229], v[72:75]
	v_mfma_f32_16x16x32_bf16 v[68:71], v[194:197], v[234:237], v[68:71]
	v_mfma_f32_16x16x32_bf16 v[64:67], v[202:205], v[234:237], v[64:67]
	s_setprio 0
	s_setprio 1
	v_mfma_f32_16x16x32_bf16 v[104:107], v[198:201], v[214:217], v[104:107]
	v_mfma_f32_16x16x32_bf16 v[96:99], v[206:209], v[214:217], v[96:99]
	v_mfma_f32_16x16x32_bf16 v[88:91], v[198:201], v[222:225], v[88:91]
	v_mfma_f32_16x16x32_bf16 v[80:83], v[206:209], v[222:225], v[80:83]
	v_mfma_f32_16x16x32_bf16 v[76:79], v[198:201], v[230:233], v[76:79]
	v_mfma_f32_16x16x32_bf16 v[72:75], v[206:209], v[230:233], v[72:75]
	v_mfma_f32_16x16x32_bf16 v[68:71], v[198:201], v[238:241], v[68:71]
	v_mfma_f32_16x16x32_bf16 v[64:67], v[206:209], v[238:241], v[64:67]
	s_setprio 0
	s_barrier
; #define PG8_STAGE(bufoff, gbase, voff) do { _Pragma("unroll") for (int _i = 0; _i < 2; ++_i) \
;         __builtin_amdgcn_global_load_lds((const unsigned*)((const char*)(gbase) + (voff)[_i]), (LAS unsigned*)(lds + (bufoff) + ldsw + _i * 8192), 16, 0, 0); } while (0)
; #define PG8_LDA(dst, b, h) do { _Pragma("unroll") for (int m = 0; m < 4; ++m) _Pragma("unroll") for (int k = 0; k < 2; ++k) dst[m][k] = *(const LAS bf16x8*)(lds + PG8_SA(b, h) + aoff + m * 2048 + k * 1024); } while (0)
; #define PG8_MMA(ai, bj, At, Bt) do { __builtin_amdgcn_s_setprio(1); _Pragma("unroll") for (int m = 0; m < 4; ++m) _Pragma("unroll") for (int n = 0; n < 2; ++n) _Pragma("unroll") for (int k = 0; k < 2; ++k) \
;         acc[ai][bj][m][n] = __builtin_amdgcn_mfma_f32_16x16x32_bf16(Bt[n][k], At[m][k], acc[ai][bj][m][n], 0, 0, 0); __builtin_amdgcn_s_setprio(0); } while (0)
; #define PG8_WAIT_V(n) asm volatile("s_waitcnt vmcnt(" #n ")" ::: "memory")
; #define PG8_WAIT_L(n) asm volatile("s_waitcnt lgkmcnt(" #n ")" ::: "memory")
; #define PG8_BAR __builtin_amdgcn_s_barrier()
; #define PG8_SCHED __builtin_amdgcn_sched_barrier(0)
; template <class Epi, class Sched>
; __device__ __forceinline__ void gemm_phase(LAS unsigned char* lds, const Gemm g, const Sched& S, const Epi& E, const int wave_s) {
;     ...
;             PG8_LDA(At, 1, 1); PG8_STAGE(PG8_SB(1, 0), b3, voffB); PG8_STAGE(PG8_SB(1, 1), b3 + hstepB, voffB); PG8_STAGE(PG8_SA(1, 0), a3, voffA);
;             PG8_WAIT_V(8); PG8_WAIT_L(0); PG8_BAR; PG8_MMA(1, 0, At, B0); PG8_MMA(1, 1, At, B1); PG8_BAR; PG8_SCHED;
;         }
	s_add_i32 s50, s73, s81
	v_lshl_add_u64 v[242:243], v[242:243], 0, s[22:23]
	s_mov_b32 m0, s50
	ds_read_b128 v[210:213], v180 offset:49152
	ds_read_b128 v[214:217], v180 offset:50176
	ds_read_b128 v[218:221], v180 offset:51200
	ds_read_b128 v[222:225], v180 offset:52224
	ds_read_b128 v[226:229], v180 offset:53248
	ds_read_b128 v[230:233], v180 offset:54272
	ds_read_b128 v[234:237], v180 offset:55296
	ds_read_b128 v[238:241], v180 offset:56320
	global_load_lds_dwordx4 v[242:243], off
	s_add_i32 m0, s50, 0x2000
	s_add_u32 s48, s48, 0x40080
	v_lshl_add_u64 v[242:243], v[244:245], 0, s[22:23]
	s_addc_u32 s49, s49, 0
	s_add_i32 s50, s74, s81
	global_load_lds_dwordx4 v[242:243], off
	v_lshl_add_u64 v[242:243], s[48:49], 0, v[130:131]
	s_mov_b32 m0, s50
	s_nop 0
	global_load_lds_dwordx4 v[242:243], off
	v_lshl_add_u64 v[242:243], s[48:49], 0, v[132:133]
	s_add_i32 m0, s50, 0x2000
	s_nop 0
	global_load_lds_dwordx4 v[242:243], off
	v_lshl_add_u64 v[242:243], v[246:247], 0, s[22:23]
	s_mov_b32 m0, s20
	s_nop 0
	global_load_lds_dwordx4 v[242:243], off
	v_lshl_add_u64 v[242:243], v[248:249], 0, s[22:23]
	s_mov_b32 m0, s63
	s_nop 0
	global_load_lds_dwordx4 v[242:243], off
	s_waitcnt vmcnt(8) lgkmcnt(0)
	s_barrier
	s_setprio 1
	v_mfma_f32_16x16x32_bf16 v[60:63], v[170:173], v[210:213], v[60:63]
	v_mfma_f32_16x16x32_bf16 v[56:59], v[186:189], v[210:213], v[56:59]
	v_mfma_f32_16x16x32_bf16 v[52:55], v[170:173], v[218:221], v[52:55]
	v_mfma_f32_16x16x32_bf16 v[48:51], v[186:189], v[218:221], v[48:51]
	v_mfma_f32_16x16x32_bf16 v[44:47], v[170:173], v[226:229], v[44:47]
	v_mfma_f32_16x16x32_bf16 v[36:39], v[186:189], v[226:229], v[36:39]
	v_mfma_f32_16x16x32_bf16 v[28:31], v[170:173], v[234:237], v[28:31]
	v_mfma_f32_16x16x32_bf16 v[20:23], v[186:189], v[234:237], v[20:23]
	s_setprio 0
	s_setprio 1
	v_mfma_f32_16x16x32_bf16 v[60:63], v[182:185], v[214:217], v[60:63]
	v_mfma_f32_16x16x32_bf16 v[56:59], v[190:193], v[214:217], v[56:59]
	v_mfma_f32_16x16x32_bf16 v[52:55], v[182:185], v[222:225], v[52:55]
	v_mfma_f32_16x16x32_bf16 v[48:51], v[190:193], v[222:225], v[48:51]
	v_mfma_f32_16x16x32_bf16 v[44:47], v[182:185], v[230:233], v[44:47]
	v_mfma_f32_16x16x32_bf16 v[36:39], v[190:193], v[230:233], v[36:39]
	v_mfma_f32_16x16x32_bf16 v[28:31], v[182:185], v[238:241], v[28:31]
	v_mfma_f32_16x16x32_bf16 v[20:23], v[190:193], v[238:241], v[20:23]
	s_setprio 0
	s_setprio 1
	v_mfma_f32_16x16x32_bf16 v[40:43], v[194:197], v[210:213], v[40:43]
	v_mfma_f32_16x16x32_bf16 v[32:35], v[202:205], v[210:213], v[32:35]
	v_mfma_f32_16x16x32_bf16 v[24:27], v[194:197], v[218:221], v[24:27]
	v_mfma_f32_16x16x32_bf16 v[16:19], v[202:205], v[218:221], v[16:19]
	v_mfma_f32_16x16x32_bf16 v[12:15], v[194:197], v[226:229], v[12:15]
	v_mfma_f32_16x16x32_bf16 v[8:11], v[202:205], v[226:229], v[8:11]
	v_mfma_f32_16x16x32_bf16 v[4:7], v[194:197], v[234:237], v[4:7]
	v_mfma_f32_16x16x32_bf16 v[0:3], v[202:205], v[234:237], v[0:3]
	s_setprio 0
	s_setprio 1
	v_mfma_f32_16x16x32_bf16 v[40:43], v[198:201], v[214:217], v[40:43]
	v_mfma_f32_16x16x32_bf16 v[32:35], v[206:209], v[214:217], v[32:35]
	v_mfma_f32_16x16x32_bf16 v[24:27], v[198:201], v[222:225], v[24:27]
	v_mfma_f32_16x16x32_bf16 v[16:19], v[206:209], v[222:225], v[16:19]
	v_mfma_f32_16x16x32_bf16 v[12:15], v[198:201], v[230:233], v[12:15]
	v_mfma_f32_16x16x32_bf16 v[8:11], v[206:209], v[230:233], v[8:11]
	v_mfma_f32_16x16x32_bf16 v[4:7], v[198:201], v[238:241], v[4:7]
	v_mfma_f32_16x16x32_bf16 v[0:3], v[206:209], v[238:241], v[0:3]
	s_setprio 0
	s_barrier
	s_add_i32 s72, s72, 2
	s_add_u32 s46, s46, 0x100
	s_addc_u32 s47, s47, 0
	s_cmp_gt_u32 s72, 13
	s_cbranch_scc0 .LBB0_1024
	s_and_b64 vcc, exec, s[12:13]
	s_cbranch_vccz .LBB0_1027
	s_barrier
